# GEMM K-loops: barrier in front of each MFMA block moved behind its first 4 MFMAs (keeps matrix pipe fed across the barrier); attention loop LDS prefetch + softmax VALU interleave
# speedup vs baseline: 1.0122x; 1.0063x over previous
.LBB0_168:
	s_add_u32 s46, s66, 0xfff80080
	s_addc_u32 s47, s67, -1
	s_add_i32 s62, 0, 0x10000
	s_cmp_eq_u32 s82, 28
	s_cselect_b32 s69, s17, s47
	s_cselect_b32 s68, s65, s46
	v_add_u32_e32 v143, s62, v140
	s_cselect_b32 s61, s13, s81
	s_cselect_b32 s60, s79, s80
	s_add_i32 s63, 0, 0x14000
	ds_read_b128 v[144:147], v143
	ds_read_b128 v[148:151], v143 offset:1024
	ds_read_b128 v[152:155], v143 offset:2048
	ds_read_b128 v[156:159], v143 offset:3072
	v_add_u32_e32 v143, s63, v140
	ds_read_b128 v[160:163], v143
	ds_read_b128 v[178:181], v143 offset:1024
	ds_read_b128 v[182:185], v143 offset:2048
	ds_read_b128 v[186:189], v143 offset:3072
	v_lshl_add_u64 v[164:165], s[66:67], 0, v[136:137]
	s_add_i32 m0, s19, 0xc000
	ds_read_b128 v[206:209], v142
	ds_read_b128 v[210:213], v142 offset:1024
	ds_read_b128 v[214:217], v142 offset:2048
	ds_read_b128 v[218:221], v142 offset:3072
	ds_read_b128 v[222:225], v142 offset:4096
	ds_read_b128 v[226:229], v142 offset:5120
	ds_read_b128 v[230:233], v142 offset:6144
	ds_read_b128 v[234:237], v142 offset:7168
	global_load_lds_dwordx4 v[164:165], off
	v_lshl_add_u64 v[164:165], s[66:67], 0, v[138:139]
	s_add_i32 m0, s19, 0xe000
	s_nop 0
	global_load_lds_dwordx4 v[164:165], off
	s_waitcnt vmcnt(8)
	s_waitcnt lgkmcnt(0)
	s_setprio 1
	s_waitcnt lgkmcnt(0)
	v_mfma_f32_16x16x32_bf16 v[126:129], v[144:147], v[206:209], v[126:129]
	v_mfma_f32_16x16x32_bf16 v[122:125], v[152:155], v[206:209], v[122:125]
	v_mfma_f32_16x16x32_bf16 v[118:121], v[144:147], v[214:217], v[118:121]
	v_mfma_f32_16x16x32_bf16 v[114:117], v[152:155], v[214:217], v[114:117]
	s_barrier
	v_mfma_f32_16x16x32_bf16 v[102:105], v[144:147], v[222:225], v[102:105]
	v_mfma_f32_16x16x32_bf16 v[98:101], v[152:155], v[222:225], v[98:101]
	v_mfma_f32_16x16x32_bf16 v[86:89], v[144:147], v[230:233], v[86:89]
	v_mfma_f32_16x16x32_bf16 v[82:85], v[152:155], v[230:233], v[82:85]
	v_mfma_f32_16x16x32_bf16 v[126:129], v[148:151], v[210:213], v[126:129]
	v_mfma_f32_16x16x32_bf16 v[122:125], v[156:159], v[210:213], v[122:125]
	v_mfma_f32_16x16x32_bf16 v[118:121], v[148:151], v[218:221], v[118:121]
	v_mfma_f32_16x16x32_bf16 v[114:117], v[156:159], v[218:221], v[114:117]
	v_mfma_f32_16x16x32_bf16 v[102:105], v[148:151], v[226:229], v[102:105]
	v_mfma_f32_16x16x32_bf16 v[98:101], v[156:159], v[226:229], v[98:101]
	v_mfma_f32_16x16x32_bf16 v[86:89], v[148:151], v[234:237], v[86:89]
	v_mfma_f32_16x16x32_bf16 v[82:85], v[156:159], v[234:237], v[82:85]
	s_setprio 0
	s_setprio 1
	v_mfma_f32_16x16x32_bf16 v[110:113], v[160:163], v[206:209], v[110:113]
	v_mfma_f32_16x16x32_bf16 v[106:109], v[182:185], v[206:209], v[106:109]
	v_mfma_f32_16x16x32_bf16 v[94:97], v[160:163], v[214:217], v[94:97]
	v_mfma_f32_16x16x32_bf16 v[90:93], v[182:185], v[214:217], v[90:93]
	v_mfma_f32_16x16x32_bf16 v[78:81], v[160:163], v[222:225], v[78:81]
	v_mfma_f32_16x16x32_bf16 v[74:77], v[182:185], v[222:225], v[74:77]
	v_mfma_f32_16x16x32_bf16 v[70:73], v[160:163], v[230:233], v[70:73]
	v_mfma_f32_16x16x32_bf16 v[66:69], v[182:185], v[230:233], v[66:69]
	v_mfma_f32_16x16x32_bf16 v[110:113], v[178:181], v[210:213], v[110:113]
	v_mfma_f32_16x16x32_bf16 v[106:109], v[186:189], v[210:213], v[106:109]
	v_mfma_f32_16x16x32_bf16 v[94:97], v[178:181], v[218:221], v[94:97]
	v_mfma_f32_16x16x32_bf16 v[90:93], v[186:189], v[218:221], v[90:93]
	v_mfma_f32_16x16x32_bf16 v[78:81], v[178:181], v[226:229], v[78:81]
	v_mfma_f32_16x16x32_bf16 v[74:77], v[186:189], v[226:229], v[74:77]
	v_mfma_f32_16x16x32_bf16 v[70:73], v[178:181], v[234:237], v[70:73]
	v_mfma_f32_16x16x32_bf16 v[66:69], v[186:189], v[234:237], v[66:69]
	s_setprio 0
	s_barrier
	s_add_i32 s46, s62, s71
	v_lshl_add_u64 v[164:165], s[60:61], 0, v[166:167]
	s_mov_b32 m0, s46
	ds_read_b128 v[206:209], v142 offset:16384
	ds_read_b128 v[210:213], v142 offset:17408
	ds_read_b128 v[214:217], v142 offset:18432
	ds_read_b128 v[218:221], v142 offset:19456
	ds_read_b128 v[222:225], v142 offset:20480
	ds_read_b128 v[226:229], v142 offset:21504
	ds_read_b128 v[230:233], v142 offset:22528
	ds_read_b128 v[234:237], v142 offset:23552
	global_load_lds_dwordx4 v[164:165], off
	s_add_i32 m0, s46, 0x2000
	s_add_u32 s46, s60, 0x80000
	v_lshl_add_u64 v[242:243], s[60:61], 0, v[130:131]
	s_addc_u32 s47, s61, 0
	s_add_i32 s62, s63, s71
	global_load_lds_dwordx4 v[242:243], off
	v_lshl_add_u64 v[244:245], s[46:47], 0, v[166:167]
	s_mov_b32 m0, s62
	v_lshl_add_u64 v[246:247], s[68:69], 0, v[132:133]
	global_load_lds_dwordx4 v[244:245], off
	v_lshl_add_u64 v[244:245], s[46:47], 0, v[130:131]
	s_add_i32 m0, s62, 0x2000
	s_nop 0
	global_load_lds_dwordx4 v[244:245], off
	v_lshl_add_u64 v[244:245], s[68:69], 0, v[134:135]
	s_mov_b32 m0, s19
	s_nop 0
	global_load_lds_dwordx4 v[244:245], off
	s_mov_b32 m0, s73
	s_nop 0
	global_load_lds_dwordx4 v[246:247], off
	s_waitcnt vmcnt(8)
	s_waitcnt lgkmcnt(0)
	s_setprio 1
	s_waitcnt lgkmcnt(0)
	v_mfma_f32_16x16x32_bf16 v[62:65], v[144:147], v[206:209], v[62:65]
	v_mfma_f32_16x16x32_bf16 v[58:61], v[152:155], v[206:209], v[58:61]
	v_mfma_f32_16x16x32_bf16 v[54:57], v[144:147], v[214:217], v[54:57]
	v_mfma_f32_16x16x32_bf16 v[50:53], v[152:155], v[214:217], v[50:53]
	s_barrier
	v_mfma_f32_16x16x32_bf16 v[38:41], v[144:147], v[222:225], v[38:41]
	v_mfma_f32_16x16x32_bf16 v[34:37], v[152:155], v[222:225], v[34:37]
	v_mfma_f32_16x16x32_bf16 v[22:25], v[144:147], v[230:233], v[22:25]
	v_mfma_f32_16x16x32_bf16 v[18:21], v[152:155], v[230:233], v[18:21]
	v_mfma_f32_16x16x32_bf16 v[62:65], v[148:151], v[210:213], v[62:65]
	v_mfma_f32_16x16x32_bf16 v[58:61], v[156:159], v[210:213], v[58:61]
	v_mfma_f32_16x16x32_bf16 v[54:57], v[148:151], v[218:221], v[54:57]
	v_mfma_f32_16x16x32_bf16 v[50:53], v[156:159], v[218:221], v[50:53]
	v_mfma_f32_16x16x32_bf16 v[38:41], v[148:151], v[226:229], v[38:41]
	v_mfma_f32_16x16x32_bf16 v[34:37], v[156:159], v[226:229], v[34:37]
	v_mfma_f32_16x16x32_bf16 v[22:25], v[148:151], v[234:237], v[22:25]
	v_mfma_f32_16x16x32_bf16 v[18:21], v[156:159], v[234:237], v[18:21]
	s_setprio 0
	s_setprio 1
	v_mfma_f32_16x16x32_bf16 v[46:49], v[160:163], v[206:209], v[46:49]
	v_mfma_f32_16x16x32_bf16 v[42:45], v[182:185], v[206:209], v[42:45]
	v_mfma_f32_16x16x32_bf16 v[30:33], v[160:163], v[214:217], v[30:33]
	v_mfma_f32_16x16x32_bf16 v[26:29], v[182:185], v[214:217], v[26:29]
	v_mfma_f32_16x16x32_bf16 v[14:17], v[160:163], v[222:225], v[14:17]
	v_mfma_f32_16x16x32_bf16 v[10:13], v[182:185], v[222:225], v[10:13]
	v_mfma_f32_16x16x32_bf16 v[6:9], v[160:163], v[230:233], v[6:9]
	v_mfma_f32_16x16x32_bf16 v[2:5], v[182:185], v[230:233], v[2:5]
	v_mfma_f32_16x16x32_bf16 v[46:49], v[178:181], v[210:213], v[46:49]
	v_mfma_f32_16x16x32_bf16 v[42:45], v[186:189], v[210:213], v[42:45]
	v_mfma_f32_16x16x32_bf16 v[30:33], v[178:181], v[218:221], v[30:33]
	v_mfma_f32_16x16x32_bf16 v[26:29], v[186:189], v[218:221], v[26:29]
	v_mfma_f32_16x16x32_bf16 v[14:17], v[178:181], v[226:229], v[14:17]
	v_mfma_f32_16x16x32_bf16 v[10:13], v[186:189], v[226:229], v[10:13]
	v_mfma_f32_16x16x32_bf16 v[6:9], v[178:181], v[234:237], v[6:9]
	v_mfma_f32_16x16x32_bf16 v[2:5], v[186:189], v[234:237], v[2:5]
	s_setprio 0
	s_barrier
	s_add_i32 s62, 0, 0x18000
	v_add_u32_e32 v143, s62, v140
	s_add_i32 s63, 0, 0x1c000
	ds_read_b128 v[144:147], v143
	ds_read_b128 v[148:151], v143 offset:1024
	ds_read_b128 v[152:155], v143 offset:2048
	ds_read_b128 v[156:159], v143 offset:3072
	v_add_u32_e32 v143, s63, v140
	ds_read_b128 v[160:163], v143
	ds_read_b128 v[178:181], v143 offset:1024
	ds_read_b128 v[182:185], v143 offset:2048
	ds_read_b128 v[186:189], v143 offset:3072
	s_add_u32 s46, s68, 0x80000
	s_addc_u32 s47, s69, 0
	s_mov_b32 m0, s74
	v_lshl_add_u64 v[248:249], s[46:47], 0, v[134:135]
	ds_read_b128 v[206:209], v142 offset:32768
	ds_read_b128 v[210:213], v142 offset:33792
	ds_read_b128 v[214:217], v142 offset:34816
	ds_read_b128 v[218:221], v142 offset:35840
	ds_read_b128 v[222:225], v142 offset:36864
	ds_read_b128 v[226:229], v142 offset:37888
	ds_read_b128 v[230:233], v142 offset:38912
	ds_read_b128 v[234:237], v142 offset:39936
	global_load_lds_dwordx4 v[248:249], off
	v_lshl_add_u64 v[248:249], s[46:47], 0, v[132:133]
	s_mov_b32 m0, s75
	s_nop 0
	global_load_lds_dwordx4 v[248:249], off
	s_waitcnt vmcnt(8)
	s_waitcnt lgkmcnt(0)
	s_setprio 1
	s_waitcnt lgkmcnt(0)
	v_mfma_f32_16x16x32_bf16 v[126:129], v[144:147], v[206:209], v[126:129]
	v_mfma_f32_16x16x32_bf16 v[122:125], v[152:155], v[206:209], v[122:125]
	v_mfma_f32_16x16x32_bf16 v[118:121], v[144:147], v[214:217], v[118:121]
	v_mfma_f32_16x16x32_bf16 v[114:117], v[152:155], v[214:217], v[114:117]
	s_barrier
	v_mfma_f32_16x16x32_bf16 v[102:105], v[144:147], v[222:225], v[102:105]
	v_mfma_f32_16x16x32_bf16 v[98:101], v[152:155], v[222:225], v[98:101]
	v_mfma_f32_16x16x32_bf16 v[86:89], v[144:147], v[230:233], v[86:89]
	v_mfma_f32_16x16x32_bf16 v[82:85], v[152:155], v[230:233], v[82:85]
	v_mfma_f32_16x16x32_bf16 v[126:129], v[148:151], v[210:213], v[126:129]
	v_mfma_f32_16x16x32_bf16 v[122:125], v[156:159], v[210:213], v[122:125]
	v_mfma_f32_16x16x32_bf16 v[118:121], v[148:151], v[218:221], v[118:121]
	v_mfma_f32_16x16x32_bf16 v[114:117], v[156:159], v[218:221], v[114:117]
	v_mfma_f32_16x16x32_bf16 v[102:105], v[148:151], v[226:229], v[102:105]
	v_mfma_f32_16x16x32_bf16 v[98:101], v[156:159], v[226:229], v[98:101]
	v_mfma_f32_16x16x32_bf16 v[86:89], v[148:151], v[234:237], v[86:89]
	v_mfma_f32_16x16x32_bf16 v[82:85], v[156:159], v[234:237], v[82:85]
	s_setprio 0
	s_setprio 1
	v_mfma_f32_16x16x32_bf16 v[110:113], v[160:163], v[206:209], v[110:113]
	v_mfma_f32_16x16x32_bf16 v[106:109], v[182:185], v[206:209], v[106:109]
	v_mfma_f32_16x16x32_bf16 v[94:97], v[160:163], v[214:217], v[94:97]
	v_mfma_f32_16x16x32_bf16 v[90:93], v[182:185], v[214:217], v[90:93]
	v_mfma_f32_16x16x32_bf16 v[78:81], v[160:163], v[222:225], v[78:81]
	v_mfma_f32_16x16x32_bf16 v[74:77], v[182:185], v[222:225], v[74:77]
	v_mfma_f32_16x16x32_bf16 v[70:73], v[160:163], v[230:233], v[70:73]
	v_mfma_f32_16x16x32_bf16 v[66:69], v[182:185], v[230:233], v[66:69]
	v_mfma_f32_16x16x32_bf16 v[110:113], v[178:181], v[210:213], v[110:113]
	v_mfma_f32_16x16x32_bf16 v[106:109], v[186:189], v[210:213], v[106:109]
	v_mfma_f32_16x16x32_bf16 v[94:97], v[178:181], v[218:221], v[94:97]
	v_mfma_f32_16x16x32_bf16 v[90:93], v[186:189], v[218:221], v[90:93]
	v_mfma_f32_16x16x32_bf16 v[78:81], v[178:181], v[226:229], v[78:81]
	v_mfma_f32_16x16x32_bf16 v[74:77], v[186:189], v[226:229], v[74:77]
	v_mfma_f32_16x16x32_bf16 v[70:73], v[178:181], v[234:237], v[70:73]
	v_mfma_f32_16x16x32_bf16 v[66:69], v[186:189], v[234:237], v[66:69]
	s_setprio 0
	s_barrier
	s_add_i32 s46, s62, s71
	v_lshl_add_u64 v[164:165], v[164:165], 0, s[42:43]
	s_mov_b32 m0, s46
	ds_read_b128 v[206:209], v142 offset:49152
	ds_read_b128 v[210:213], v142 offset:50176
	ds_read_b128 v[214:217], v142 offset:51200
	ds_read_b128 v[218:221], v142 offset:52224
	ds_read_b128 v[222:225], v142 offset:53248
	ds_read_b128 v[226:229], v142 offset:54272
	ds_read_b128 v[230:233], v142 offset:55296
	ds_read_b128 v[234:237], v142 offset:56320
	global_load_lds_dwordx4 v[164:165], off
	s_add_i32 m0, s46, 0x2000
	s_add_u32 s46, s60, 0x80080
	v_lshl_add_u64 v[164:165], v[242:243], 0, s[42:43]
	s_addc_u32 s47, s61, 0
	s_add_i32 s60, s63, s71
	global_load_lds_dwordx4 v[164:165], off
	v_lshl_add_u64 v[164:165], s[46:47], 0, v[166:167]
	s_mov_b32 m0, s60
	s_nop 0
	global_load_lds_dwordx4 v[164:165], off
	v_lshl_add_u64 v[164:165], s[46:47], 0, v[130:131]
	s_add_i32 m0, s60, 0x2000
	s_nop 0
	global_load_lds_dwordx4 v[164:165], off
	v_lshl_add_u64 v[164:165], v[244:245], 0, s[42:43]
	s_mov_b32 m0, s76
	s_nop 0
	global_load_lds_dwordx4 v[164:165], off
	v_lshl_add_u64 v[164:165], v[246:247], 0, s[42:43]
	s_mov_b32 m0, s77
	s_nop 0
	global_load_lds_dwordx4 v[164:165], off
	s_waitcnt vmcnt(8)
	s_waitcnt lgkmcnt(0)
	s_setprio 1
	s_waitcnt lgkmcnt(0)
	v_mfma_f32_16x16x32_bf16 v[62:65], v[144:147], v[206:209], v[62:65]
	v_mfma_f32_16x16x32_bf16 v[58:61], v[152:155], v[206:209], v[58:61]
	v_mfma_f32_16x16x32_bf16 v[54:57], v[144:147], v[214:217], v[54:57]
	v_mfma_f32_16x16x32_bf16 v[50:53], v[152:155], v[214:217], v[50:53]
	s_barrier
	v_mfma_f32_16x16x32_bf16 v[38:41], v[144:147], v[222:225], v[38:41]
	v_mfma_f32_16x16x32_bf16 v[34:37], v[152:155], v[222:225], v[34:37]
	v_mfma_f32_16x16x32_bf16 v[22:25], v[144:147], v[230:233], v[22:25]
	v_mfma_f32_16x16x32_bf16 v[18:21], v[152:155], v[230:233], v[18:21]
	v_mfma_f32_16x16x32_bf16 v[62:65], v[148:151], v[210:213], v[62:65]
	v_mfma_f32_16x16x32_bf16 v[58:61], v[156:159], v[210:213], v[58:61]
	v_mfma_f32_16x16x32_bf16 v[54:57], v[148:151], v[218:221], v[54:57]
	v_mfma_f32_16x16x32_bf16 v[50:53], v[156:159], v[218:221], v[50:53]
	v_mfma_f32_16x16x32_bf16 v[38:41], v[148:151], v[226:229], v[38:41]
	v_mfma_f32_16x16x32_bf16 v[34:37], v[156:159], v[226:229], v[34:37]
	v_mfma_f32_16x16x32_bf16 v[22:25], v[148:151], v[234:237], v[22:25]
	v_mfma_f32_16x16x32_bf16 v[18:21], v[156:159], v[234:237], v[18:21]
	s_setprio 0
	s_setprio 1
	v_mfma_f32_16x16x32_bf16 v[46:49], v[160:163], v[206:209], v[46:49]
	v_mfma_f32_16x16x32_bf16 v[42:45], v[182:185], v[206:209], v[42:45]
	v_mfma_f32_16x16x32_bf16 v[30:33], v[160:163], v[214:217], v[30:33]
	v_mfma_f32_16x16x32_bf16 v[26:29], v[182:185], v[214:217], v[26:29]
	v_mfma_f32_16x16x32_bf16 v[14:17], v[160:163], v[222:225], v[14:17]
	v_mfma_f32_16x16x32_bf16 v[10:13], v[182:185], v[222:225], v[10:13]
	v_mfma_f32_16x16x32_bf16 v[6:9], v[160:163], v[230:233], v[6:9]
	v_mfma_f32_16x16x32_bf16 v[2:5], v[182:185], v[230:233], v[2:5]
	v_mfma_f32_16x16x32_bf16 v[46:49], v[178:181], v[210:213], v[46:49]
	v_mfma_f32_16x16x32_bf16 v[42:45], v[186:189], v[210:213], v[42:45]
	v_mfma_f32_16x16x32_bf16 v[30:33], v[178:181], v[218:221], v[30:33]
	v_mfma_f32_16x16x32_bf16 v[26:29], v[186:189], v[218:221], v[26:29]
	v_mfma_f32_16x16x32_bf16 v[14:17], v[178:181], v[226:229], v[14:17]
	v_mfma_f32_16x16x32_bf16 v[10:13], v[186:189], v[226:229], v[10:13]
	v_mfma_f32_16x16x32_bf16 v[6:9], v[178:181], v[234:237], v[6:9]
	v_mfma_f32_16x16x32_bf16 v[2:5], v[186:189], v[234:237], v[2:5]
	s_setprio 0
	s_barrier
	s_add_i32 s82, s82, 2
	s_add_u32 s66, s66, 0x100
	s_addc_u32 s67, s67, 0
	s_add_u32 s80, s80, 0x100
	s_addc_u32 s81, s81, 0
	s_cmp_gt_u32 s82, 29
	s_cbranch_scc0 .LBB0_168
	s_and_b64 vcc, exec, s[10:11]
	s_cbranch_vccz .LBB0_171
	s_barrier

.LBB0_426:
	s_add_u32 s46, s66, 0xfffe0080
	s_addc_u32 s47, s67, -1
	s_add_i32 s62, 0, 0x10000
	s_cmp_eq_u32 s84, 4
	s_cselect_b32 s69, s19, s47
	s_cselect_b32 s68, s80, s46
	v_add_u32_e32 v143, s62, v140
	s_cselect_b32 s61, s17, s83
	s_cselect_b32 s60, s81, s82
	s_add_i32 s63, 0, 0x14000
	ds_read_b128 v[144:147], v143
	ds_read_b128 v[148:151], v143 offset:1024
	ds_read_b128 v[152:155], v143 offset:2048
	ds_read_b128 v[156:159], v143 offset:3072
	v_add_u32_e32 v143, s63, v140
	ds_read_b128 v[160:163], v143
	ds_read_b128 v[178:181], v143 offset:1024
	ds_read_b128 v[182:185], v143 offset:2048
	ds_read_b128 v[186:189], v143 offset:3072
	v_lshl_add_u64 v[164:165], s[66:67], 0, v[136:137]
	s_add_i32 m0, s11, 0xc000
	ds_read_b128 v[206:209], v142
	ds_read_b128 v[210:213], v142 offset:1024
	ds_read_b128 v[214:217], v142 offset:2048
	ds_read_b128 v[218:221], v142 offset:3072
	ds_read_b128 v[222:225], v142 offset:4096
	ds_read_b128 v[226:229], v142 offset:5120
	ds_read_b128 v[230:233], v142 offset:6144
	ds_read_b128 v[234:237], v142 offset:7168
	global_load_lds_dwordx4 v[164:165], off
	v_lshl_add_u64 v[164:165], s[66:67], 0, v[138:139]
	s_add_i32 m0, s11, 0xe000
	s_nop 0
	global_load_lds_dwordx4 v[164:165], off
	s_waitcnt vmcnt(8)
	s_waitcnt lgkmcnt(0)
	s_setprio 1
	s_waitcnt lgkmcnt(0)
	v_mfma_f32_16x16x32_bf16 v[126:129], v[144:147], v[206:209], v[126:129]
	v_mfma_f32_16x16x32_bf16 v[122:125], v[152:155], v[206:209], v[122:125]
	v_mfma_f32_16x16x32_bf16 v[118:121], v[144:147], v[214:217], v[118:121]
	v_mfma_f32_16x16x32_bf16 v[114:117], v[152:155], v[214:217], v[114:117]
	s_barrier
	v_mfma_f32_16x16x32_bf16 v[102:105], v[144:147], v[222:225], v[102:105]
	v_mfma_f32_16x16x32_bf16 v[98:101], v[152:155], v[222:225], v[98:101]
	v_mfma_f32_16x16x32_bf16 v[86:89], v[144:147], v[230:233], v[86:89]
	v_mfma_f32_16x16x32_bf16 v[82:85], v[152:155], v[230:233], v[82:85]
	v_mfma_f32_16x16x32_bf16 v[126:129], v[148:151], v[210:213], v[126:129]
	v_mfma_f32_16x16x32_bf16 v[122:125], v[156:159], v[210:213], v[122:125]
	v_mfma_f32_16x16x32_bf16 v[118:121], v[148:151], v[218:221], v[118:121]
	v_mfma_f32_16x16x32_bf16 v[114:117], v[156:159], v[218:221], v[114:117]
	v_mfma_f32_16x16x32_bf16 v[102:105], v[148:151], v[226:229], v[102:105]
	v_mfma_f32_16x16x32_bf16 v[98:101], v[156:159], v[226:229], v[98:101]
	v_mfma_f32_16x16x32_bf16 v[86:89], v[148:151], v[234:237], v[86:89]
	v_mfma_f32_16x16x32_bf16 v[82:85], v[156:159], v[234:237], v[82:85]
	s_setprio 0
	s_setprio 1
	v_mfma_f32_16x16x32_bf16 v[110:113], v[160:163], v[206:209], v[110:113]
	v_mfma_f32_16x16x32_bf16 v[106:109], v[182:185], v[206:209], v[106:109]
	v_mfma_f32_16x16x32_bf16 v[94:97], v[160:163], v[214:217], v[94:97]
	v_mfma_f32_16x16x32_bf16 v[90:93], v[182:185], v[214:217], v[90:93]
	v_mfma_f32_16x16x32_bf16 v[78:81], v[160:163], v[222:225], v[78:81]
	v_mfma_f32_16x16x32_bf16 v[74:77], v[182:185], v[222:225], v[74:77]
	v_mfma_f32_16x16x32_bf16 v[70:73], v[160:163], v[230:233], v[70:73]
	v_mfma_f32_16x16x32_bf16 v[66:69], v[182:185], v[230:233], v[66:69]
	v_mfma_f32_16x16x32_bf16 v[110:113], v[178:181], v[210:213], v[110:113]
	v_mfma_f32_16x16x32_bf16 v[106:109], v[186:189], v[210:213], v[106:109]
	v_mfma_f32_16x16x32_bf16 v[94:97], v[178:181], v[218:221], v[94:97]
	v_mfma_f32_16x16x32_bf16 v[90:93], v[186:189], v[218:221], v[90:93]
	v_mfma_f32_16x16x32_bf16 v[78:81], v[178:181], v[226:229], v[78:81]
	v_mfma_f32_16x16x32_bf16 v[74:77], v[186:189], v[226:229], v[74:77]
	v_mfma_f32_16x16x32_bf16 v[70:73], v[178:181], v[234:237], v[70:73]
	v_mfma_f32_16x16x32_bf16 v[66:69], v[186:189], v[234:237], v[66:69]
	s_setprio 0
	s_barrier
	s_add_i32 s46, s62, s72
	v_lshl_add_u64 v[164:165], s[60:61], 0, v[166:167]
	s_mov_b32 m0, s46
	ds_read_b128 v[206:209], v142 offset:16384
	ds_read_b128 v[210:213], v142 offset:17408
	ds_read_b128 v[214:217], v142 offset:18432
	ds_read_b128 v[218:221], v142 offset:19456
	ds_read_b128 v[222:225], v142 offset:20480
	ds_read_b128 v[226:229], v142 offset:21504
	ds_read_b128 v[230:233], v142 offset:22528
	ds_read_b128 v[234:237], v142 offset:23552
	global_load_lds_dwordx4 v[164:165], off
	s_add_i32 m0, s46, 0x2000
	s_add_u32 s46, s60, 0x20000
	v_lshl_add_u64 v[242:243], s[60:61], 0, v[130:131]
	s_addc_u32 s47, s61, 0
	s_add_i32 s62, s63, s72
	global_load_lds_dwordx4 v[242:243], off
	v_lshl_add_u64 v[244:245], s[46:47], 0, v[166:167]
	s_mov_b32 m0, s62
	v_lshl_add_u64 v[246:247], s[68:69], 0, v[132:133]
	global_load_lds_dwordx4 v[244:245], off
	v_lshl_add_u64 v[244:245], s[46:47], 0, v[130:131]
	s_add_i32 m0, s62, 0x2000
	s_nop 0
	global_load_lds_dwordx4 v[244:245], off
	v_lshl_add_u64 v[244:245], s[68:69], 0, v[134:135]
	s_mov_b32 m0, s11
	s_nop 0
	global_load_lds_dwordx4 v[244:245], off
	s_mov_b32 m0, s74
	s_nop 0
	global_load_lds_dwordx4 v[246:247], off
	s_waitcnt vmcnt(8)
	s_waitcnt lgkmcnt(0)
	s_setprio 1
	s_waitcnt lgkmcnt(0)
	v_mfma_f32_16x16x32_bf16 v[62:65], v[144:147], v[206:209], v[62:65]
	v_mfma_f32_16x16x32_bf16 v[58:61], v[152:155], v[206:209], v[58:61]
	v_mfma_f32_16x16x32_bf16 v[54:57], v[144:147], v[214:217], v[54:57]
	v_mfma_f32_16x16x32_bf16 v[50:53], v[152:155], v[214:217], v[50:53]
	s_barrier
	v_mfma_f32_16x16x32_bf16 v[38:41], v[144:147], v[222:225], v[38:41]
	v_mfma_f32_16x16x32_bf16 v[34:37], v[152:155], v[222:225], v[34:37]
	v_mfma_f32_16x16x32_bf16 v[22:25], v[144:147], v[230:233], v[22:25]
	v_mfma_f32_16x16x32_bf16 v[18:21], v[152:155], v[230:233], v[18:21]
	v_mfma_f32_16x16x32_bf16 v[62:65], v[148:151], v[210:213], v[62:65]
	v_mfma_f32_16x16x32_bf16 v[58:61], v[156:159], v[210:213], v[58:61]
	v_mfma_f32_16x16x32_bf16 v[54:57], v[148:151], v[218:221], v[54:57]
	v_mfma_f32_16x16x32_bf16 v[50:53], v[156:159], v[218:221], v[50:53]
	v_mfma_f32_16x16x32_bf16 v[38:41], v[148:151], v[226:229], v[38:41]
	v_mfma_f32_16x16x32_bf16 v[34:37], v[156:159], v[226:229], v[34:37]
	v_mfma_f32_16x16x32_bf16 v[22:25], v[148:151], v[234:237], v[22:25]
	v_mfma_f32_16x16x32_bf16 v[18:21], v[156:159], v[234:237], v[18:21]
	s_setprio 0
	s_setprio 1
	v_mfma_f32_16x16x32_bf16 v[46:49], v[160:163], v[206:209], v[46:49]
	v_mfma_f32_16x16x32_bf16 v[42:45], v[182:185], v[206:209], v[42:45]
	v_mfma_f32_16x16x32_bf16 v[30:33], v[160:163], v[214:217], v[30:33]
	v_mfma_f32_16x16x32_bf16 v[26:29], v[182:185], v[214:217], v[26:29]
	v_mfma_f32_16x16x32_bf16 v[14:17], v[160:163], v[222:225], v[14:17]
	v_mfma_f32_16x16x32_bf16 v[10:13], v[182:185], v[222:225], v[10:13]
	v_mfma_f32_16x16x32_bf16 v[6:9], v[160:163], v[230:233], v[6:9]
	v_mfma_f32_16x16x32_bf16 v[2:5], v[182:185], v[230:233], v[2:5]
	v_mfma_f32_16x16x32_bf16 v[46:49], v[178:181], v[210:213], v[46:49]
	v_mfma_f32_16x16x32_bf16 v[42:45], v[186:189], v[210:213], v[42:45]
	v_mfma_f32_16x16x32_bf16 v[30:33], v[178:181], v[218:221], v[30:33]
	v_mfma_f32_16x16x32_bf16 v[26:29], v[186:189], v[218:221], v[26:29]
	v_mfma_f32_16x16x32_bf16 v[14:17], v[178:181], v[226:229], v[14:17]
	v_mfma_f32_16x16x32_bf16 v[10:13], v[186:189], v[226:229], v[10:13]
	v_mfma_f32_16x16x32_bf16 v[6:9], v[178:181], v[234:237], v[6:9]
	v_mfma_f32_16x16x32_bf16 v[2:5], v[186:189], v[234:237], v[2:5]
	s_setprio 0
	s_barrier
	s_add_i32 s62, 0, 0x18000
	v_add_u32_e32 v143, s62, v140
	s_add_i32 s63, 0, 0x1c000
	ds_read_b128 v[144:147], v143
	ds_read_b128 v[148:151], v143 offset:1024
	ds_read_b128 v[152:155], v143 offset:2048
	ds_read_b128 v[156:159], v143 offset:3072
	v_add_u32_e32 v143, s63, v140
	ds_read_b128 v[160:163], v143
	ds_read_b128 v[178:181], v143 offset:1024
	ds_read_b128 v[182:185], v143 offset:2048
	ds_read_b128 v[186:189], v143 offset:3072
	s_add_u32 s46, s68, 0x20000
	s_addc_u32 s47, s69, 0
	s_mov_b32 m0, s75
	v_lshl_add_u64 v[248:249], s[46:47], 0, v[134:135]
	ds_read_b128 v[206:209], v142 offset:32768
	ds_read_b128 v[210:213], v142 offset:33792
	ds_read_b128 v[214:217], v142 offset:34816
	ds_read_b128 v[218:221], v142 offset:35840
	ds_read_b128 v[222:225], v142 offset:36864
	ds_read_b128 v[226:229], v142 offset:37888
	ds_read_b128 v[230:233], v142 offset:38912
	ds_read_b128 v[234:237], v142 offset:39936
	global_load_lds_dwordx4 v[248:249], off
	v_lshl_add_u64 v[248:249], s[46:47], 0, v[132:133]
	s_mov_b32 m0, s76
	s_nop 0
	global_load_lds_dwordx4 v[248:249], off
	s_waitcnt vmcnt(8)
	s_waitcnt lgkmcnt(0)
	s_setprio 1
	s_waitcnt lgkmcnt(0)
	v_mfma_f32_16x16x32_bf16 v[126:129], v[144:147], v[206:209], v[126:129]
	v_mfma_f32_16x16x32_bf16 v[122:125], v[152:155], v[206:209], v[122:125]
	v_mfma_f32_16x16x32_bf16 v[118:121], v[144:147], v[214:217], v[118:121]
	v_mfma_f32_16x16x32_bf16 v[114:117], v[152:155], v[214:217], v[114:117]
	s_barrier
	v_mfma_f32_16x16x32_bf16 v[102:105], v[144:147], v[222:225], v[102:105]
	v_mfma_f32_16x16x32_bf16 v[98:101], v[152:155], v[222:225], v[98:101]
	v_mfma_f32_16x16x32_bf16 v[86:89], v[144:147], v[230:233], v[86:89]
	v_mfma_f32_16x16x32_bf16 v[82:85], v[152:155], v[230:233], v[82:85]
	v_mfma_f32_16x16x32_bf16 v[126:129], v[148:151], v[210:213], v[126:129]
	v_mfma_f32_16x16x32_bf16 v[122:125], v[156:159], v[210:213], v[122:125]
	v_mfma_f32_16x16x32_bf16 v[118:121], v[148:151], v[218:221], v[118:121]
	v_mfma_f32_16x16x32_bf16 v[114:117], v[156:159], v[218:221], v[114:117]
	v_mfma_f32_16x16x32_bf16 v[102:105], v[148:151], v[226:229], v[102:105]
	v_mfma_f32_16x16x32_bf16 v[98:101], v[156:159], v[226:229], v[98:101]
	v_mfma_f32_16x16x32_bf16 v[86:89], v[148:151], v[234:237], v[86:89]
	v_mfma_f32_16x16x32_bf16 v[82:85], v[156:159], v[234:237], v[82:85]
	s_setprio 0
	s_setprio 1
	v_mfma_f32_16x16x32_bf16 v[110:113], v[160:163], v[206:209], v[110:113]
	v_mfma_f32_16x16x32_bf16 v[106:109], v[182:185], v[206:209], v[106:109]
	v_mfma_f32_16x16x32_bf16 v[94:97], v[160:163], v[214:217], v[94:97]
	v_mfma_f32_16x16x32_bf16 v[90:93], v[182:185], v[214:217], v[90:93]
	v_mfma_f32_16x16x32_bf16 v[78:81], v[160:163], v[222:225], v[78:81]
	v_mfma_f32_16x16x32_bf16 v[74:77], v[182:185], v[222:225], v[74:77]
	v_mfma_f32_16x16x32_bf16 v[70:73], v[160:163], v[230:233], v[70:73]
	v_mfma_f32_16x16x32_bf16 v[66:69], v[182:185], v[230:233], v[66:69]
	v_mfma_f32_16x16x32_bf16 v[110:113], v[178:181], v[210:213], v[110:113]
	v_mfma_f32_16x16x32_bf16 v[106:109], v[186:189], v[210:213], v[106:109]
	v_mfma_f32_16x16x32_bf16 v[94:97], v[178:181], v[218:221], v[94:97]
	v_mfma_f32_16x16x32_bf16 v[90:93], v[186:189], v[218:221], v[90:93]
	v_mfma_f32_16x16x32_bf16 v[78:81], v[178:181], v[226:229], v[78:81]
	v_mfma_f32_16x16x32_bf16 v[74:77], v[186:189], v[226:229], v[74:77]
	v_mfma_f32_16x16x32_bf16 v[70:73], v[178:181], v[234:237], v[70:73]
	v_mfma_f32_16x16x32_bf16 v[66:69], v[186:189], v[234:237], v[66:69]
	s_setprio 0
	s_barrier
	s_add_i32 s46, s62, s72
	v_lshl_add_u64 v[164:165], v[164:165], 0, s[42:43]
	s_mov_b32 m0, s46
	ds_read_b128 v[206:209], v142 offset:49152
	ds_read_b128 v[210:213], v142 offset:50176
	ds_read_b128 v[214:217], v142 offset:51200
	ds_read_b128 v[218:221], v142 offset:52224
	ds_read_b128 v[222:225], v142 offset:53248
	ds_read_b128 v[226:229], v142 offset:54272
	ds_read_b128 v[230:233], v142 offset:55296
	ds_read_b128 v[234:237], v142 offset:56320
	global_load_lds_dwordx4 v[164:165], off
	s_add_i32 m0, s46, 0x2000
	s_add_u32 s46, s60, 0x20080
	v_lshl_add_u64 v[164:165], v[242:243], 0, s[42:43]
	s_addc_u32 s47, s61, 0
	s_add_i32 s60, s63, s72
	global_load_lds_dwordx4 v[164:165], off
	v_lshl_add_u64 v[164:165], s[46:47], 0, v[166:167]
	s_mov_b32 m0, s60
	s_nop 0
	global_load_lds_dwordx4 v[164:165], off
	v_lshl_add_u64 v[164:165], s[46:47], 0, v[130:131]
	s_add_i32 m0, s60, 0x2000
	s_nop 0
	global_load_lds_dwordx4 v[164:165], off
	v_lshl_add_u64 v[164:165], v[244:245], 0, s[42:43]
	s_mov_b32 m0, s77
	s_nop 0
	global_load_lds_dwordx4 v[164:165], off
	v_lshl_add_u64 v[164:165], v[246:247], 0, s[42:43]
	s_mov_b32 m0, s78
	s_nop 0
	global_load_lds_dwordx4 v[164:165], off
	s_waitcnt vmcnt(8)
	s_waitcnt lgkmcnt(0)
	s_setprio 1
	s_waitcnt lgkmcnt(0)
	v_mfma_f32_16x16x32_bf16 v[62:65], v[144:147], v[206:209], v[62:65]
	v_mfma_f32_16x16x32_bf16 v[58:61], v[152:155], v[206:209], v[58:61]
	v_mfma_f32_16x16x32_bf16 v[54:57], v[144:147], v[214:217], v[54:57]
	v_mfma_f32_16x16x32_bf16 v[50:53], v[152:155], v[214:217], v[50:53]
	s_barrier
	v_mfma_f32_16x16x32_bf16 v[38:41], v[144:147], v[222:225], v[38:41]
	v_mfma_f32_16x16x32_bf16 v[34:37], v[152:155], v[222:225], v[34:37]
	v_mfma_f32_16x16x32_bf16 v[22:25], v[144:147], v[230:233], v[22:25]
	v_mfma_f32_16x16x32_bf16 v[18:21], v[152:155], v[230:233], v[18:21]
	v_mfma_f32_16x16x32_bf16 v[62:65], v[148:151], v[210:213], v[62:65]
	v_mfma_f32_16x16x32_bf16 v[58:61], v[156:159], v[210:213], v[58:61]
	v_mfma_f32_16x16x32_bf16 v[54:57], v[148:151], v[218:221], v[54:57]
	v_mfma_f32_16x16x32_bf16 v[50:53], v[156:159], v[218:221], v[50:53]
	v_mfma_f32_16x16x32_bf16 v[38:41], v[148:151], v[226:229], v[38:41]
	v_mfma_f32_16x16x32_bf16 v[34:37], v[156:159], v[226:229], v[34:37]
	v_mfma_f32_16x16x32_bf16 v[22:25], v[148:151], v[234:237], v[22:25]
	v_mfma_f32_16x16x32_bf16 v[18:21], v[156:159], v[234:237], v[18:21]
	s_setprio 0
	s_setprio 1
	v_mfma_f32_16x16x32_bf16 v[46:49], v[160:163], v[206:209], v[46:49]
	v_mfma_f32_16x16x32_bf16 v[42:45], v[182:185], v[206:209], v[42:45]
	v_mfma_f32_16x16x32_bf16 v[30:33], v[160:163], v[214:217], v[30:33]
	v_mfma_f32_16x16x32_bf16 v[26:29], v[182:185], v[214:217], v[26:29]
	v_mfma_f32_16x16x32_bf16 v[14:17], v[160:163], v[222:225], v[14:17]
	v_mfma_f32_16x16x32_bf16 v[10:13], v[182:185], v[222:225], v[10:13]
	v_mfma_f32_16x16x32_bf16 v[6:9], v[160:163], v[230:233], v[6:9]
	v_mfma_f32_16x16x32_bf16 v[2:5], v[182:185], v[230:233], v[2:5]
	v_mfma_f32_16x16x32_bf16 v[46:49], v[178:181], v[210:213], v[46:49]
	v_mfma_f32_16x16x32_bf16 v[42:45], v[186:189], v[210:213], v[42:45]
	v_mfma_f32_16x16x32_bf16 v[30:33], v[178:181], v[218:221], v[30:33]
	v_mfma_f32_16x16x32_bf16 v[26:29], v[186:189], v[218:221], v[26:29]
	v_mfma_f32_16x16x32_bf16 v[14:17], v[178:181], v[226:229], v[14:17]
	v_mfma_f32_16x16x32_bf16 v[10:13], v[186:189], v[226:229], v[10:13]
	v_mfma_f32_16x16x32_bf16 v[6:9], v[178:181], v[234:237], v[6:9]
	v_mfma_f32_16x16x32_bf16 v[2:5], v[186:189], v[234:237], v[2:5]
	s_setprio 0
	s_barrier
	s_add_i32 s84, s84, 2
	s_add_u32 s66, s66, 0x100
	s_addc_u32 s67, s67, 0
	s_add_u32 s82, s82, 0x100
	s_addc_u32 s83, s83, 0
	s_cmp_gt_u32 s84, 5
	s_cbranch_scc0 .LBB0_426
	s_and_b64 vcc, exec, s[12:13]
	s_cbranch_vccz .LBB0_429
	s_barrier

.LBB0_442:
	s_add_u32 s62, s18, s72
	s_addc_u32 s63, s19, 0
	s_add_u32 s73, s62, 0x100
	s_addc_u32 s74, s63, 0
	s_and_b64 s[46:47], s[60:61], exec
	s_cselect_b32 s75, s23, s74
	s_cselect_b32 s74, s92, s73
	s_add_u32 s46, s16, s72
	s_addc_u32 s47, s17, 0
	s_add_u32 s72, s46, 0x100
	s_addc_u32 s73, s47, 0
	s_add_i32 s48, 0, 0x10000
	s_and_b64 s[46:47], s[60:61], exec
	s_cselect_b32 s77, s21, s73
	s_cselect_b32 s76, s93, s72
	s_add_i32 s46, 0, 0x14000
	s_add_u32 s80, s62, 0x10080
	s_addc_u32 s81, s63, 0
	s_add_i32 s63, s48, s84
	s_add_i32 m0, s13, 0xc000
	s_add_i32 s49, s13, 0xe000
	s_add_i32 vcc_lo, s63, 0x2000
	v_add_u32_e32 v139, s48, v136
	s_add_u32 s78, s76, 0x10000
	ds_read_b128 v[140:143], v139
	ds_read_b128 v[144:147], v139 offset:1024
	ds_read_b128 v[148:151], v139 offset:2048
	ds_read_b128 v[152:155], v139 offset:3072
	v_add_u32_e32 v139, s46, v136
	s_addc_u32 s79, s77, 0
	s_add_i32 vcc_hi, s46, s84
	ds_read_b128 v[156:159], v139
	ds_read_b128 v[160:163], v139 offset:1024
	ds_read_b128 v[178:181], v139 offset:2048
	ds_read_b128 v[182:185], v139 offset:3072
	s_add_i32 s62, vcc_hi, 0x2000
	s_add_i32 s97, 0, 0x18000
	s_add_i32 s96, 0, 0x1c000
	s_add_u32 s72, s74, 0x10000
	s_addc_u32 s73, s75, 0
	s_add_i32 s95, s97, s84
	s_add_i32 s94, s95, 0x2000
	s_add_u32 s60, s76, 0x10080
	s_addc_u32 s61, s77, 0
	s_add_i32 s47, s96, s84
	s_add_i32 s46, s47, 0x2000
	v_lshl_add_u64 v[164:165], s[80:81], 0, v[134:135]
	ds_read_b128 v[186:189], v138
	ds_read_b128 v[206:209], v138 offset:1024
	ds_read_b128 v[210:213], v138 offset:2048
	ds_read_b128 v[214:217], v138 offset:3072
	ds_read_b128 v[218:221], v138 offset:4096
	ds_read_b128 v[222:225], v138 offset:5120
	ds_read_b128 v[226:229], v138 offset:6144
	ds_read_b128 v[230:233], v138 offset:7168
	global_load_lds_dwordx4 v[164:165], off
	v_lshl_add_u64 v[164:165], s[80:81], 0, v[132:133]
	s_mov_b32 m0, s49
	s_nop 0
	global_load_lds_dwordx4 v[164:165], off
	s_waitcnt vmcnt(8)
	s_waitcnt lgkmcnt(0)
	s_setprio 1
	s_waitcnt lgkmcnt(0)
	v_mfma_f32_16x16x32_bf16 v[126:129], v[140:143], v[186:189], v[126:129]
	v_mfma_f32_16x16x32_bf16 v[122:125], v[148:151], v[186:189], v[122:125]
	v_mfma_f32_16x16x32_bf16 v[118:121], v[140:143], v[210:213], v[118:121]
	v_mfma_f32_16x16x32_bf16 v[114:117], v[148:151], v[210:213], v[114:117]
	s_barrier
	v_mfma_f32_16x16x32_bf16 v[102:105], v[140:143], v[218:221], v[102:105]
	v_mfma_f32_16x16x32_bf16 v[98:101], v[148:151], v[218:221], v[98:101]
	v_mfma_f32_16x16x32_bf16 v[86:89], v[140:143], v[226:229], v[86:89]
	v_mfma_f32_16x16x32_bf16 v[82:85], v[148:151], v[226:229], v[82:85]
	v_mfma_f32_16x16x32_bf16 v[126:129], v[144:147], v[206:209], v[126:129]
	v_mfma_f32_16x16x32_bf16 v[122:125], v[152:155], v[206:209], v[122:125]
	v_mfma_f32_16x16x32_bf16 v[118:121], v[144:147], v[214:217], v[118:121]
	v_mfma_f32_16x16x32_bf16 v[114:117], v[152:155], v[214:217], v[114:117]
	v_mfma_f32_16x16x32_bf16 v[102:105], v[144:147], v[222:225], v[102:105]
	v_mfma_f32_16x16x32_bf16 v[98:101], v[152:155], v[222:225], v[98:101]
	v_mfma_f32_16x16x32_bf16 v[86:89], v[144:147], v[230:233], v[86:89]
	v_mfma_f32_16x16x32_bf16 v[82:85], v[152:155], v[230:233], v[82:85]
	s_setprio 0
	s_setprio 1
	v_mfma_f32_16x16x32_bf16 v[110:113], v[156:159], v[186:189], v[110:113]
	v_mfma_f32_16x16x32_bf16 v[106:109], v[178:181], v[186:189], v[106:109]
	v_mfma_f32_16x16x32_bf16 v[94:97], v[156:159], v[210:213], v[94:97]
	v_mfma_f32_16x16x32_bf16 v[90:93], v[178:181], v[210:213], v[90:93]
	v_mfma_f32_16x16x32_bf16 v[78:81], v[156:159], v[218:221], v[78:81]
	v_mfma_f32_16x16x32_bf16 v[74:77], v[178:181], v[218:221], v[74:77]
	v_mfma_f32_16x16x32_bf16 v[70:73], v[156:159], v[226:229], v[70:73]
	v_mfma_f32_16x16x32_bf16 v[66:69], v[178:181], v[226:229], v[66:69]
	v_mfma_f32_16x16x32_bf16 v[110:113], v[160:163], v[206:209], v[110:113]
	v_mfma_f32_16x16x32_bf16 v[106:109], v[182:185], v[206:209], v[106:109]
	v_mfma_f32_16x16x32_bf16 v[94:97], v[160:163], v[214:217], v[94:97]
	v_mfma_f32_16x16x32_bf16 v[90:93], v[182:185], v[214:217], v[90:93]
	v_mfma_f32_16x16x32_bf16 v[78:81], v[160:163], v[222:225], v[78:81]
	v_mfma_f32_16x16x32_bf16 v[74:77], v[182:185], v[222:225], v[74:77]
	v_mfma_f32_16x16x32_bf16 v[70:73], v[160:163], v[230:233], v[70:73]
	v_mfma_f32_16x16x32_bf16 v[66:69], v[182:185], v[230:233], v[66:69]
	s_setprio 0
	s_barrier
	s_mov_b32 m0, s63
	v_lshl_add_u64 v[164:165], s[76:77], 0, v[166:167]
	ds_read_b128 v[186:189], v138 offset:16384
	ds_read_b128 v[206:209], v138 offset:17408
	ds_read_b128 v[210:213], v138 offset:18432
	ds_read_b128 v[214:217], v138 offset:19456
	ds_read_b128 v[218:221], v138 offset:20480
	ds_read_b128 v[222:225], v138 offset:21504
	ds_read_b128 v[226:229], v138 offset:22528
	ds_read_b128 v[230:233], v138 offset:23552
	global_load_lds_dwordx4 v[164:165], off
	v_lshl_add_u64 v[234:235], s[76:77], 0, v[130:131]
	s_mov_b32 m0, vcc_lo
	v_lshl_add_u64 v[236:237], s[78:79], 0, v[166:167]
	global_load_lds_dwordx4 v[234:235], off
	s_mov_b32 m0, vcc_hi
	v_lshl_add_u64 v[242:243], s[74:75], 0, v[132:133]
	global_load_lds_dwordx4 v[236:237], off
	v_lshl_add_u64 v[236:237], s[78:79], 0, v[130:131]
	s_mov_b32 m0, s62
	s_nop 0
	global_load_lds_dwordx4 v[236:237], off
	v_lshl_add_u64 v[236:237], s[74:75], 0, v[134:135]
	s_mov_b32 m0, s13
	s_nop 0
	global_load_lds_dwordx4 v[236:237], off
	s_mov_b32 m0, s86
	s_nop 0
	global_load_lds_dwordx4 v[242:243], off
	s_waitcnt vmcnt(8)
	s_waitcnt lgkmcnt(0)
	s_setprio 1
	s_waitcnt lgkmcnt(0)
	v_mfma_f32_16x16x32_bf16 v[62:65], v[140:143], v[186:189], v[62:65]
	v_mfma_f32_16x16x32_bf16 v[58:61], v[148:151], v[186:189], v[58:61]
	v_mfma_f32_16x16x32_bf16 v[54:57], v[140:143], v[210:213], v[54:57]
	v_mfma_f32_16x16x32_bf16 v[50:53], v[148:151], v[210:213], v[50:53]
	s_barrier
	v_mfma_f32_16x16x32_bf16 v[38:41], v[140:143], v[218:221], v[38:41]
	v_mfma_f32_16x16x32_bf16 v[34:37], v[148:151], v[218:221], v[34:37]
	v_mfma_f32_16x16x32_bf16 v[22:25], v[140:143], v[226:229], v[22:25]
	v_mfma_f32_16x16x32_bf16 v[18:21], v[148:151], v[226:229], v[18:21]
	v_mfma_f32_16x16x32_bf16 v[62:65], v[144:147], v[206:209], v[62:65]
	v_mfma_f32_16x16x32_bf16 v[58:61], v[152:155], v[206:209], v[58:61]
	v_mfma_f32_16x16x32_bf16 v[54:57], v[144:147], v[214:217], v[54:57]
	v_mfma_f32_16x16x32_bf16 v[50:53], v[152:155], v[214:217], v[50:53]
	v_mfma_f32_16x16x32_bf16 v[38:41], v[144:147], v[222:225], v[38:41]
	v_mfma_f32_16x16x32_bf16 v[34:37], v[152:155], v[222:225], v[34:37]
	v_mfma_f32_16x16x32_bf16 v[22:25], v[144:147], v[230:233], v[22:25]
	v_mfma_f32_16x16x32_bf16 v[18:21], v[152:155], v[230:233], v[18:21]
	s_setprio 0
	s_setprio 1
	v_mfma_f32_16x16x32_bf16 v[46:49], v[156:159], v[186:189], v[46:49]
	v_mfma_f32_16x16x32_bf16 v[42:45], v[178:181], v[186:189], v[42:45]
	v_mfma_f32_16x16x32_bf16 v[30:33], v[156:159], v[210:213], v[30:33]
	v_mfma_f32_16x16x32_bf16 v[26:29], v[178:181], v[210:213], v[26:29]
	v_mfma_f32_16x16x32_bf16 v[14:17], v[156:159], v[218:221], v[14:17]
	v_mfma_f32_16x16x32_bf16 v[10:13], v[178:181], v[218:221], v[10:13]
	v_mfma_f32_16x16x32_bf16 v[6:9], v[156:159], v[226:229], v[6:9]
	v_mfma_f32_16x16x32_bf16 v[2:5], v[178:181], v[226:229], v[2:5]
	v_mfma_f32_16x16x32_bf16 v[46:49], v[160:163], v[206:209], v[46:49]
	v_mfma_f32_16x16x32_bf16 v[42:45], v[182:185], v[206:209], v[42:45]
	v_mfma_f32_16x16x32_bf16 v[30:33], v[160:163], v[214:217], v[30:33]
	v_mfma_f32_16x16x32_bf16 v[26:29], v[182:185], v[214:217], v[26:29]
	v_mfma_f32_16x16x32_bf16 v[14:17], v[160:163], v[222:225], v[14:17]
	v_mfma_f32_16x16x32_bf16 v[10:13], v[182:185], v[222:225], v[10:13]
	v_mfma_f32_16x16x32_bf16 v[6:9], v[160:163], v[230:233], v[6:9]
	v_mfma_f32_16x16x32_bf16 v[2:5], v[182:185], v[230:233], v[2:5]
	s_setprio 0
	s_barrier
	v_add_u32_e32 v139, s97, v136
	ds_read_b128 v[140:143], v139
	ds_read_b128 v[144:147], v139 offset:1024
	ds_read_b128 v[148:151], v139 offset:2048
	ds_read_b128 v[152:155], v139 offset:3072
	v_add_u32_e32 v139, s96, v136
	ds_read_b128 v[156:159], v139
	ds_read_b128 v[160:163], v139 offset:1024
	ds_read_b128 v[178:181], v139 offset:2048
	ds_read_b128 v[182:185], v139 offset:3072
	s_mov_b32 m0, s87
	v_lshl_add_u64 v[244:245], s[72:73], 0, v[134:135]
	ds_read_b128 v[186:189], v138 offset:32768
	ds_read_b128 v[206:209], v138 offset:33792
	ds_read_b128 v[210:213], v138 offset:34816
	ds_read_b128 v[214:217], v138 offset:35840
	ds_read_b128 v[218:221], v138 offset:36864
	ds_read_b128 v[222:225], v138 offset:37888
	ds_read_b128 v[226:229], v138 offset:38912
	ds_read_b128 v[230:233], v138 offset:39936
	global_load_lds_dwordx4 v[244:245], off
	v_lshl_add_u64 v[244:245], s[72:73], 0, v[132:133]
	s_mov_b32 m0, s88
	s_nop 0
	global_load_lds_dwordx4 v[244:245], off
	s_waitcnt vmcnt(8)
	s_waitcnt lgkmcnt(0)
	s_setprio 1
	s_waitcnt lgkmcnt(0)
	v_mfma_f32_16x16x32_bf16 v[126:129], v[140:143], v[186:189], v[126:129]
	v_mfma_f32_16x16x32_bf16 v[122:125], v[148:151], v[186:189], v[122:125]
	v_mfma_f32_16x16x32_bf16 v[118:121], v[140:143], v[210:213], v[118:121]
	v_mfma_f32_16x16x32_bf16 v[114:117], v[148:151], v[210:213], v[114:117]
	s_barrier
	v_mfma_f32_16x16x32_bf16 v[102:105], v[140:143], v[218:221], v[102:105]
	v_mfma_f32_16x16x32_bf16 v[98:101], v[148:151], v[218:221], v[98:101]
	v_mfma_f32_16x16x32_bf16 v[86:89], v[140:143], v[226:229], v[86:89]
	v_mfma_f32_16x16x32_bf16 v[82:85], v[148:151], v[226:229], v[82:85]
	v_mfma_f32_16x16x32_bf16 v[126:129], v[144:147], v[206:209], v[126:129]
	v_mfma_f32_16x16x32_bf16 v[122:125], v[152:155], v[206:209], v[122:125]
	v_mfma_f32_16x16x32_bf16 v[118:121], v[144:147], v[214:217], v[118:121]
	v_mfma_f32_16x16x32_bf16 v[114:117], v[152:155], v[214:217], v[114:117]
	v_mfma_f32_16x16x32_bf16 v[102:105], v[144:147], v[222:225], v[102:105]
	v_mfma_f32_16x16x32_bf16 v[98:101], v[152:155], v[222:225], v[98:101]
	v_mfma_f32_16x16x32_bf16 v[86:89], v[144:147], v[230:233], v[86:89]
	v_mfma_f32_16x16x32_bf16 v[82:85], v[152:155], v[230:233], v[82:85]
	s_setprio 0
	s_setprio 1
	v_mfma_f32_16x16x32_bf16 v[110:113], v[156:159], v[186:189], v[110:113]
	v_mfma_f32_16x16x32_bf16 v[106:109], v[178:181], v[186:189], v[106:109]
	v_mfma_f32_16x16x32_bf16 v[94:97], v[156:159], v[210:213], v[94:97]
	v_mfma_f32_16x16x32_bf16 v[90:93], v[178:181], v[210:213], v[90:93]
	v_mfma_f32_16x16x32_bf16 v[78:81], v[156:159], v[218:221], v[78:81]
	v_mfma_f32_16x16x32_bf16 v[74:77], v[178:181], v[218:221], v[74:77]
	v_mfma_f32_16x16x32_bf16 v[70:73], v[156:159], v[226:229], v[70:73]
	v_mfma_f32_16x16x32_bf16 v[66:69], v[178:181], v[226:229], v[66:69]
	v_mfma_f32_16x16x32_bf16 v[110:113], v[160:163], v[206:209], v[110:113]
	v_mfma_f32_16x16x32_bf16 v[106:109], v[182:185], v[206:209], v[106:109]
	v_mfma_f32_16x16x32_bf16 v[94:97], v[160:163], v[214:217], v[94:97]
	v_mfma_f32_16x16x32_bf16 v[90:93], v[182:185], v[214:217], v[90:93]
	v_mfma_f32_16x16x32_bf16 v[78:81], v[160:163], v[222:225], v[78:81]
	v_mfma_f32_16x16x32_bf16 v[74:77], v[182:185], v[222:225], v[74:77]
	v_mfma_f32_16x16x32_bf16 v[70:73], v[160:163], v[230:233], v[70:73]
	v_mfma_f32_16x16x32_bf16 v[66:69], v[182:185], v[230:233], v[66:69]
	s_setprio 0
	s_barrier
	s_mov_b32 m0, s95
	v_lshl_add_u64 v[164:165], v[164:165], 0, s[42:43]
	ds_read_b128 v[186:189], v138 offset:49152
	ds_read_b128 v[206:209], v138 offset:50176
	ds_read_b128 v[210:213], v138 offset:51200
	ds_read_b128 v[214:217], v138 offset:52224
	ds_read_b128 v[218:221], v138 offset:53248
	ds_read_b128 v[222:225], v138 offset:54272
	ds_read_b128 v[226:229], v138 offset:55296
	ds_read_b128 v[230:233], v138 offset:56320
	global_load_lds_dwordx4 v[164:165], off
	v_lshl_add_u64 v[164:165], v[234:235], 0, s[42:43]
	s_mov_b32 m0, s94
	s_nop 0
	global_load_lds_dwordx4 v[164:165], off
	v_lshl_add_u64 v[164:165], s[60:61], 0, v[166:167]
	s_mov_b32 m0, s47
	s_nop 0
	global_load_lds_dwordx4 v[164:165], off
	v_lshl_add_u64 v[164:165], s[60:61], 0, v[130:131]
	s_mov_b32 m0, s46
	s_nop 0
	global_load_lds_dwordx4 v[164:165], off
	v_lshl_add_u64 v[164:165], v[236:237], 0, s[42:43]
	s_mov_b32 m0, s89
	s_nop 0
	global_load_lds_dwordx4 v[164:165], off
	v_lshl_add_u64 v[164:165], v[242:243], 0, s[42:43]
	s_mov_b32 m0, s90
	s_nop 0
	global_load_lds_dwordx4 v[164:165], off
	s_waitcnt vmcnt(8)
	s_waitcnt lgkmcnt(0)
	s_setprio 1
	s_waitcnt lgkmcnt(0)
	v_mfma_f32_16x16x32_bf16 v[62:65], v[140:143], v[186:189], v[62:65]
	v_mfma_f32_16x16x32_bf16 v[58:61], v[148:151], v[186:189], v[58:61]
	v_mfma_f32_16x16x32_bf16 v[54:57], v[140:143], v[210:213], v[54:57]
	v_mfma_f32_16x16x32_bf16 v[50:53], v[148:151], v[210:213], v[50:53]
	s_barrier
	v_mfma_f32_16x16x32_bf16 v[38:41], v[140:143], v[218:221], v[38:41]
	v_mfma_f32_16x16x32_bf16 v[34:37], v[148:151], v[218:221], v[34:37]
	v_mfma_f32_16x16x32_bf16 v[22:25], v[140:143], v[226:229], v[22:25]
	v_mfma_f32_16x16x32_bf16 v[18:21], v[148:151], v[226:229], v[18:21]
	v_mfma_f32_16x16x32_bf16 v[62:65], v[144:147], v[206:209], v[62:65]
	v_mfma_f32_16x16x32_bf16 v[58:61], v[152:155], v[206:209], v[58:61]
	v_mfma_f32_16x16x32_bf16 v[54:57], v[144:147], v[214:217], v[54:57]
	v_mfma_f32_16x16x32_bf16 v[50:53], v[152:155], v[214:217], v[50:53]
	v_mfma_f32_16x16x32_bf16 v[38:41], v[144:147], v[222:225], v[38:41]
	v_mfma_f32_16x16x32_bf16 v[34:37], v[152:155], v[222:225], v[34:37]
	v_mfma_f32_16x16x32_bf16 v[22:25], v[144:147], v[230:233], v[22:25]
	v_mfma_f32_16x16x32_bf16 v[18:21], v[152:155], v[230:233], v[18:21]
	s_setprio 0
	s_setprio 1
	v_mfma_f32_16x16x32_bf16 v[46:49], v[156:159], v[186:189], v[46:49]
	v_mfma_f32_16x16x32_bf16 v[42:45], v[178:181], v[186:189], v[42:45]
	v_mfma_f32_16x16x32_bf16 v[30:33], v[156:159], v[210:213], v[30:33]
	v_mfma_f32_16x16x32_bf16 v[26:29], v[178:181], v[210:213], v[26:29]
	v_mfma_f32_16x16x32_bf16 v[14:17], v[156:159], v[218:221], v[14:17]
	v_mfma_f32_16x16x32_bf16 v[10:13], v[178:181], v[218:221], v[10:13]
	v_mfma_f32_16x16x32_bf16 v[6:9], v[156:159], v[226:229], v[6:9]
	v_mfma_f32_16x16x32_bf16 v[2:5], v[178:181], v[226:229], v[2:5]
	v_mfma_f32_16x16x32_bf16 v[46:49], v[160:163], v[206:209], v[46:49]
	v_mfma_f32_16x16x32_bf16 v[42:45], v[182:185], v[206:209], v[42:45]
	v_mfma_f32_16x16x32_bf16 v[30:33], v[160:163], v[214:217], v[30:33]
	v_mfma_f32_16x16x32_bf16 v[26:29], v[182:185], v[214:217], v[26:29]
	v_mfma_f32_16x16x32_bf16 v[14:17], v[160:163], v[222:225], v[14:17]
	v_mfma_f32_16x16x32_bf16 v[10:13], v[182:185], v[222:225], v[10:13]
	v_mfma_f32_16x16x32_bf16 v[6:9], v[160:163], v[230:233], v[6:9]
	v_mfma_f32_16x16x32_bf16 v[2:5], v[182:185], v[230:233], v[2:5]
	s_setprio 0
	s_barrier
	s_movk_i32 s72, 0x100
	s_andn2_b64 vcc, exec, s[70:71]
	s_mov_b64 s[60:61], -1
	s_mov_b64 s[70:71], 0
	s_cbranch_vccz .LBB0_442
	s_and_b64 vcc, exec, s[10:11]
	s_cbranch_vccz .LBB0_445
	s_barrier

.LBB0_795:
	s_add_u32 s46, s68, 0xfff80080
	s_addc_u32 s47, s69, -1
	s_add_i32 s48, 0, 0x10000
	s_cmp_eq_u32 s87, 28
	s_cselect_b32 s71, s19, s47
	s_cselect_b32 s70, s83, s46
	s_cselect_b32 s61, s17, s86
	s_cselect_b32 s60, s84, s85
	s_add_i32 s49, 0, 0x14000
	v_add_u32_e32 v156, s48, v1
	v_add_u32_e32 v164, s49, v1
	ds_read_b128 v[130:133], v156
	ds_read_b128 v[134:137], v156 offset:1024
	ds_read_b128 v[150:153], v156 offset:2048
	ds_read_b128 v[156:159], v156 offset:3072
	ds_read_b128 v[160:163], v164
	ds_read_b128 v[178:181], v164 offset:1024
	ds_read_b128 v[182:185], v164 offset:2048
	ds_read_b128 v[186:189], v164 offset:3072
	v_lshl_add_u64 v[164:165], s[68:69], 0, v[146:147]
	s_add_i32 m0, s67, 0xc000
	ds_read_b128 v[206:209], v155
	ds_read_b128 v[210:213], v155 offset:1024
	ds_read_b128 v[214:217], v155 offset:2048
	ds_read_b128 v[218:221], v155 offset:3072
	ds_read_b128 v[222:225], v155 offset:4096
	ds_read_b128 v[226:229], v155 offset:5120
	ds_read_b128 v[230:233], v155 offset:6144
	ds_read_b128 v[234:237], v155 offset:7168
	global_load_lds_dwordx4 v[164:165], off
	v_lshl_add_u64 v[164:165], s[68:69], 0, v[148:149]
	s_add_i32 m0, s67, 0xe000
	s_nop 0
	global_load_lds_dwordx4 v[164:165], off
	s_waitcnt vmcnt(8)
	s_waitcnt lgkmcnt(0)
	s_setprio 1
	s_waitcnt lgkmcnt(0)
	v_mfma_f32_16x16x32_bf16 v[126:129], v[130:133], v[206:209], v[126:129]
	v_mfma_f32_16x16x32_bf16 v[122:125], v[150:153], v[206:209], v[122:125]
	v_mfma_f32_16x16x32_bf16 v[118:121], v[130:133], v[214:217], v[118:121]
	v_mfma_f32_16x16x32_bf16 v[114:117], v[150:153], v[214:217], v[114:117]
	s_barrier
	v_mfma_f32_16x16x32_bf16 v[110:113], v[130:133], v[222:225], v[110:113]
	v_mfma_f32_16x16x32_bf16 v[106:109], v[150:153], v[222:225], v[106:109]
	v_mfma_f32_16x16x32_bf16 v[102:105], v[130:133], v[230:233], v[102:105]
	v_mfma_f32_16x16x32_bf16 v[98:101], v[150:153], v[230:233], v[98:101]
	v_mfma_f32_16x16x32_bf16 v[126:129], v[134:137], v[210:213], v[126:129]
	v_mfma_f32_16x16x32_bf16 v[122:125], v[156:159], v[210:213], v[122:125]
	v_mfma_f32_16x16x32_bf16 v[118:121], v[134:137], v[218:221], v[118:121]
	v_mfma_f32_16x16x32_bf16 v[114:117], v[156:159], v[218:221], v[114:117]
	v_mfma_f32_16x16x32_bf16 v[110:113], v[134:137], v[226:229], v[110:113]
	v_mfma_f32_16x16x32_bf16 v[106:109], v[156:159], v[226:229], v[106:109]
	v_mfma_f32_16x16x32_bf16 v[102:105], v[134:137], v[234:237], v[102:105]
	v_mfma_f32_16x16x32_bf16 v[98:101], v[156:159], v[234:237], v[98:101]
	s_setprio 0
	s_setprio 1
	v_mfma_f32_16x16x32_bf16 v[66:69], v[160:163], v[206:209], v[66:69]
	v_mfma_f32_16x16x32_bf16 v[58:61], v[182:185], v[206:209], v[58:61]
	v_mfma_f32_16x16x32_bf16 v[54:57], v[160:163], v[214:217], v[54:57]
	v_mfma_f32_16x16x32_bf16 v[50:53], v[182:185], v[214:217], v[50:53]
	v_mfma_f32_16x16x32_bf16 v[46:49], v[160:163], v[222:225], v[46:49]
	v_mfma_f32_16x16x32_bf16 v[42:45], v[182:185], v[222:225], v[42:45]
	v_mfma_f32_16x16x32_bf16 v[38:41], v[160:163], v[230:233], v[38:41]
	v_mfma_f32_16x16x32_bf16 v[34:37], v[182:185], v[230:233], v[34:37]
	v_mfma_f32_16x16x32_bf16 v[66:69], v[178:181], v[210:213], v[66:69]
	v_mfma_f32_16x16x32_bf16 v[58:61], v[186:189], v[210:213], v[58:61]
	v_mfma_f32_16x16x32_bf16 v[54:57], v[178:181], v[218:221], v[54:57]
	v_mfma_f32_16x16x32_bf16 v[50:53], v[186:189], v[218:221], v[50:53]
	v_mfma_f32_16x16x32_bf16 v[46:49], v[178:181], v[226:229], v[46:49]
	v_mfma_f32_16x16x32_bf16 v[42:45], v[186:189], v[226:229], v[42:45]
	v_mfma_f32_16x16x32_bf16 v[38:41], v[178:181], v[234:237], v[38:41]
	v_mfma_f32_16x16x32_bf16 v[34:37], v[186:189], v[234:237], v[34:37]
	s_setprio 0
	s_barrier
	s_add_i32 s46, s48, s77
	v_lshl_add_u64 v[164:165], s[60:61], 0, v[166:167]
	s_mov_b32 m0, s46
	ds_read_b128 v[206:209], v155 offset:16384
	ds_read_b128 v[210:213], v155 offset:17408
	ds_read_b128 v[214:217], v155 offset:18432
	ds_read_b128 v[218:221], v155 offset:19456
	ds_read_b128 v[222:225], v155 offset:20480
	ds_read_b128 v[226:229], v155 offset:21504
	ds_read_b128 v[230:233], v155 offset:22528
	ds_read_b128 v[234:237], v155 offset:23552
	global_load_lds_dwordx4 v[164:165], off
	s_add_i32 m0, s46, 0x2000
	s_add_u32 s46, s60, 0x80000
	v_lshl_add_u64 v[242:243], s[60:61], 0, v[142:143]
	s_addc_u32 s47, s61, 0
	s_add_i32 s48, s49, s77
	global_load_lds_dwordx4 v[242:243], off
	v_lshl_add_u64 v[244:245], s[46:47], 0, v[166:167]
	s_mov_b32 m0, s48
	v_lshl_add_u64 v[246:247], s[70:71], 0, v[140:141]
	global_load_lds_dwordx4 v[244:245], off
	v_lshl_add_u64 v[244:245], s[46:47], 0, v[142:143]
	s_add_i32 m0, s48, 0x2000
	s_nop 0
	global_load_lds_dwordx4 v[244:245], off
	v_lshl_add_u64 v[244:245], s[70:71], 0, v[138:139]
	s_mov_b32 m0, s67
	s_nop 0
	global_load_lds_dwordx4 v[244:245], off
	s_mov_b32 m0, s78
	s_nop 0
	global_load_lds_dwordx4 v[246:247], off
	s_waitcnt vmcnt(8)
	s_waitcnt lgkmcnt(0)
	s_setprio 1
	s_waitcnt lgkmcnt(0)
	v_mfma_f32_16x16x32_bf16 v[94:97], v[130:133], v[206:209], v[94:97]
	v_mfma_f32_16x16x32_bf16 v[90:93], v[150:153], v[206:209], v[90:93]
	v_mfma_f32_16x16x32_bf16 v[86:89], v[130:133], v[214:217], v[86:89]
	v_mfma_f32_16x16x32_bf16 v[82:85], v[150:153], v[214:217], v[82:85]
	s_barrier
	v_mfma_f32_16x16x32_bf16 v[78:81], v[130:133], v[222:225], v[78:81]
	v_mfma_f32_16x16x32_bf16 v[74:77], v[150:153], v[222:225], v[74:77]
	v_mfma_f32_16x16x32_bf16 v[70:73], v[130:133], v[230:233], v[70:73]
	v_mfma_f32_16x16x32_bf16 v[62:65], v[150:153], v[230:233], v[62:65]
	v_mfma_f32_16x16x32_bf16 v[94:97], v[134:137], v[210:213], v[94:97]
	v_mfma_f32_16x16x32_bf16 v[90:93], v[156:159], v[210:213], v[90:93]
	v_mfma_f32_16x16x32_bf16 v[86:89], v[134:137], v[218:221], v[86:89]
	v_mfma_f32_16x16x32_bf16 v[82:85], v[156:159], v[218:221], v[82:85]
	v_mfma_f32_16x16x32_bf16 v[78:81], v[134:137], v[226:229], v[78:81]
	v_mfma_f32_16x16x32_bf16 v[74:77], v[156:159], v[226:229], v[74:77]
	v_mfma_f32_16x16x32_bf16 v[70:73], v[134:137], v[234:237], v[70:73]
	v_mfma_f32_16x16x32_bf16 v[62:65], v[156:159], v[234:237], v[62:65]
	s_setprio 0
	s_setprio 1
	v_mfma_f32_16x16x32_bf16 v[30:33], v[160:163], v[206:209], v[30:33]
	v_mfma_f32_16x16x32_bf16 v[26:29], v[182:185], v[206:209], v[26:29]
	v_mfma_f32_16x16x32_bf16 v[22:25], v[160:163], v[214:217], v[22:25]
	v_mfma_f32_16x16x32_bf16 v[18:21], v[182:185], v[214:217], v[18:21]
	v_mfma_f32_16x16x32_bf16 v[14:17], v[160:163], v[222:225], v[14:17]
	v_mfma_f32_16x16x32_bf16 v[10:13], v[182:185], v[222:225], v[10:13]
	v_mfma_f32_16x16x32_bf16 v[6:9], v[160:163], v[230:233], v[6:9]
	v_mfma_f32_16x16x32_bf16 v[2:5], v[182:185], v[230:233], v[2:5]
	v_mfma_f32_16x16x32_bf16 v[30:33], v[178:181], v[210:213], v[30:33]
	v_mfma_f32_16x16x32_bf16 v[26:29], v[186:189], v[210:213], v[26:29]
	v_mfma_f32_16x16x32_bf16 v[22:25], v[178:181], v[218:221], v[22:25]
	v_mfma_f32_16x16x32_bf16 v[18:21], v[186:189], v[218:221], v[18:21]
	v_mfma_f32_16x16x32_bf16 v[14:17], v[178:181], v[226:229], v[14:17]
	v_mfma_f32_16x16x32_bf16 v[10:13], v[186:189], v[226:229], v[10:13]
	v_mfma_f32_16x16x32_bf16 v[6:9], v[178:181], v[234:237], v[6:9]
	v_mfma_f32_16x16x32_bf16 v[2:5], v[186:189], v[234:237], v[2:5]
	s_setprio 0
	s_barrier
	s_add_i32 s48, 0, 0x18000
	s_add_i32 s49, 0, 0x1c000
	v_add_u32_e32 v156, s48, v1
	v_add_u32_e32 v186, s49, v1
	ds_read_b128 v[130:133], v156
	ds_read_b128 v[134:137], v156 offset:1024
	ds_read_b128 v[150:153], v156 offset:2048
	ds_read_b128 v[156:159], v156 offset:3072
	ds_read_b128 v[160:163], v186
	ds_read_b128 v[178:181], v186 offset:1024
	ds_read_b128 v[182:185], v186 offset:2048
	ds_read_b128 v[186:189], v186 offset:3072
	s_add_u32 s46, s70, 0x80000
	s_addc_u32 s47, s71, 0
	s_mov_b32 m0, s79
	v_lshl_add_u64 v[248:249], s[46:47], 0, v[138:139]
	ds_read_b128 v[206:209], v155 offset:32768
	ds_read_b128 v[210:213], v155 offset:33792
	ds_read_b128 v[214:217], v155 offset:34816
	ds_read_b128 v[218:221], v155 offset:35840
	ds_read_b128 v[222:225], v155 offset:36864
	ds_read_b128 v[226:229], v155 offset:37888
	ds_read_b128 v[230:233], v155 offset:38912
	ds_read_b128 v[234:237], v155 offset:39936
	global_load_lds_dwordx4 v[248:249], off
	v_lshl_add_u64 v[248:249], s[46:47], 0, v[140:141]
	s_mov_b32 m0, s80
	s_nop 0
	global_load_lds_dwordx4 v[248:249], off
	s_waitcnt vmcnt(8)
	s_waitcnt lgkmcnt(0)
	s_setprio 1
	s_waitcnt lgkmcnt(0)
	v_mfma_f32_16x16x32_bf16 v[126:129], v[130:133], v[206:209], v[126:129]
	v_mfma_f32_16x16x32_bf16 v[122:125], v[150:153], v[206:209], v[122:125]
	v_mfma_f32_16x16x32_bf16 v[118:121], v[130:133], v[214:217], v[118:121]
	v_mfma_f32_16x16x32_bf16 v[114:117], v[150:153], v[214:217], v[114:117]
	s_barrier
	v_mfma_f32_16x16x32_bf16 v[110:113], v[130:133], v[222:225], v[110:113]
	v_mfma_f32_16x16x32_bf16 v[106:109], v[150:153], v[222:225], v[106:109]
	v_mfma_f32_16x16x32_bf16 v[102:105], v[130:133], v[230:233], v[102:105]
	v_mfma_f32_16x16x32_bf16 v[98:101], v[150:153], v[230:233], v[98:101]
	v_mfma_f32_16x16x32_bf16 v[126:129], v[134:137], v[210:213], v[126:129]
	v_mfma_f32_16x16x32_bf16 v[122:125], v[156:159], v[210:213], v[122:125]
	v_mfma_f32_16x16x32_bf16 v[118:121], v[134:137], v[218:221], v[118:121]
	v_mfma_f32_16x16x32_bf16 v[114:117], v[156:159], v[218:221], v[114:117]
	v_mfma_f32_16x16x32_bf16 v[110:113], v[134:137], v[226:229], v[110:113]
	v_mfma_f32_16x16x32_bf16 v[106:109], v[156:159], v[226:229], v[106:109]
	v_mfma_f32_16x16x32_bf16 v[102:105], v[134:137], v[234:237], v[102:105]
	v_mfma_f32_16x16x32_bf16 v[98:101], v[156:159], v[234:237], v[98:101]
	s_setprio 0
	s_setprio 1
	v_mfma_f32_16x16x32_bf16 v[66:69], v[160:163], v[206:209], v[66:69]
	v_mfma_f32_16x16x32_bf16 v[58:61], v[182:185], v[206:209], v[58:61]
	v_mfma_f32_16x16x32_bf16 v[54:57], v[160:163], v[214:217], v[54:57]
	v_mfma_f32_16x16x32_bf16 v[50:53], v[182:185], v[214:217], v[50:53]
	v_mfma_f32_16x16x32_bf16 v[46:49], v[160:163], v[222:225], v[46:49]
	v_mfma_f32_16x16x32_bf16 v[42:45], v[182:185], v[222:225], v[42:45]
	v_mfma_f32_16x16x32_bf16 v[38:41], v[160:163], v[230:233], v[38:41]
	v_mfma_f32_16x16x32_bf16 v[34:37], v[182:185], v[230:233], v[34:37]
	v_mfma_f32_16x16x32_bf16 v[66:69], v[178:181], v[210:213], v[66:69]
	v_mfma_f32_16x16x32_bf16 v[58:61], v[186:189], v[210:213], v[58:61]
	v_mfma_f32_16x16x32_bf16 v[54:57], v[178:181], v[218:221], v[54:57]
	v_mfma_f32_16x16x32_bf16 v[50:53], v[186:189], v[218:221], v[50:53]
	v_mfma_f32_16x16x32_bf16 v[46:49], v[178:181], v[226:229], v[46:49]
	v_mfma_f32_16x16x32_bf16 v[42:45], v[186:189], v[226:229], v[42:45]
	v_mfma_f32_16x16x32_bf16 v[38:41], v[178:181], v[234:237], v[38:41]
	v_mfma_f32_16x16x32_bf16 v[34:37], v[186:189], v[234:237], v[34:37]
	s_setprio 0
	s_barrier
	s_add_i32 s46, s48, s77
	v_lshl_add_u64 v[164:165], v[164:165], 0, s[42:43]
	s_mov_b32 m0, s46
	ds_read_b128 v[206:209], v155 offset:49152
	ds_read_b128 v[210:213], v155 offset:50176
	ds_read_b128 v[214:217], v155 offset:51200
	ds_read_b128 v[218:221], v155 offset:52224
	ds_read_b128 v[222:225], v155 offset:53248
	ds_read_b128 v[226:229], v155 offset:54272
	ds_read_b128 v[230:233], v155 offset:55296
	ds_read_b128 v[234:237], v155 offset:56320
	global_load_lds_dwordx4 v[164:165], off
	s_add_i32 m0, s46, 0x2000
	s_add_u32 s46, s60, 0x80080
	v_lshl_add_u64 v[164:165], v[242:243], 0, s[42:43]
	s_addc_u32 s47, s61, 0
	s_add_i32 s48, s49, s77
	global_load_lds_dwordx4 v[164:165], off
	v_lshl_add_u64 v[164:165], s[46:47], 0, v[166:167]
	s_mov_b32 m0, s48
	s_nop 0
	global_load_lds_dwordx4 v[164:165], off
	v_lshl_add_u64 v[164:165], s[46:47], 0, v[142:143]
	s_add_i32 m0, s48, 0x2000
	s_nop 0
	global_load_lds_dwordx4 v[164:165], off
	v_lshl_add_u64 v[164:165], v[244:245], 0, s[42:43]
	s_mov_b32 m0, s26
	s_nop 0
	global_load_lds_dwordx4 v[164:165], off
	v_lshl_add_u64 v[164:165], v[246:247], 0, s[42:43]
	s_mov_b32 m0, s81
	s_nop 0
	global_load_lds_dwordx4 v[164:165], off
	s_waitcnt vmcnt(8)
	s_waitcnt lgkmcnt(0)
	s_setprio 1
	s_waitcnt lgkmcnt(0)
	v_mfma_f32_16x16x32_bf16 v[94:97], v[130:133], v[206:209], v[94:97]
	v_mfma_f32_16x16x32_bf16 v[90:93], v[150:153], v[206:209], v[90:93]
	v_mfma_f32_16x16x32_bf16 v[86:89], v[130:133], v[214:217], v[86:89]
	v_mfma_f32_16x16x32_bf16 v[82:85], v[150:153], v[214:217], v[82:85]
	s_barrier
	v_mfma_f32_16x16x32_bf16 v[78:81], v[130:133], v[222:225], v[78:81]
	v_mfma_f32_16x16x32_bf16 v[74:77], v[150:153], v[222:225], v[74:77]
	v_mfma_f32_16x16x32_bf16 v[70:73], v[130:133], v[230:233], v[70:73]
	v_mfma_f32_16x16x32_bf16 v[62:65], v[150:153], v[230:233], v[62:65]
	v_mfma_f32_16x16x32_bf16 v[94:97], v[134:137], v[210:213], v[94:97]
	v_mfma_f32_16x16x32_bf16 v[90:93], v[156:159], v[210:213], v[90:93]
	v_mfma_f32_16x16x32_bf16 v[86:89], v[134:137], v[218:221], v[86:89]
	v_mfma_f32_16x16x32_bf16 v[82:85], v[156:159], v[218:221], v[82:85]
	v_mfma_f32_16x16x32_bf16 v[78:81], v[134:137], v[226:229], v[78:81]
	v_mfma_f32_16x16x32_bf16 v[74:77], v[156:159], v[226:229], v[74:77]
	v_mfma_f32_16x16x32_bf16 v[70:73], v[134:137], v[234:237], v[70:73]
	v_mfma_f32_16x16x32_bf16 v[62:65], v[156:159], v[234:237], v[62:65]
	s_setprio 0
	s_setprio 1
	v_mfma_f32_16x16x32_bf16 v[30:33], v[160:163], v[206:209], v[30:33]
	v_mfma_f32_16x16x32_bf16 v[26:29], v[182:185], v[206:209], v[26:29]
	v_mfma_f32_16x16x32_bf16 v[22:25], v[160:163], v[214:217], v[22:25]
	v_mfma_f32_16x16x32_bf16 v[18:21], v[182:185], v[214:217], v[18:21]
	v_mfma_f32_16x16x32_bf16 v[14:17], v[160:163], v[222:225], v[14:17]
	v_mfma_f32_16x16x32_bf16 v[10:13], v[182:185], v[222:225], v[10:13]
	v_mfma_f32_16x16x32_bf16 v[6:9], v[160:163], v[230:233], v[6:9]
	v_mfma_f32_16x16x32_bf16 v[2:5], v[182:185], v[230:233], v[2:5]
	v_mfma_f32_16x16x32_bf16 v[30:33], v[178:181], v[210:213], v[30:33]
	v_mfma_f32_16x16x32_bf16 v[26:29], v[186:189], v[210:213], v[26:29]
	v_mfma_f32_16x16x32_bf16 v[22:25], v[178:181], v[218:221], v[22:25]
	v_mfma_f32_16x16x32_bf16 v[18:21], v[186:189], v[218:221], v[18:21]
	v_mfma_f32_16x16x32_bf16 v[14:17], v[178:181], v[226:229], v[14:17]
	v_mfma_f32_16x16x32_bf16 v[10:13], v[186:189], v[226:229], v[10:13]
	v_mfma_f32_16x16x32_bf16 v[6:9], v[178:181], v[234:237], v[6:9]
	v_mfma_f32_16x16x32_bf16 v[2:5], v[186:189], v[234:237], v[2:5]
	s_setprio 0
	s_barrier
	s_add_i32 s87, s87, 2
	s_add_u32 s68, s68, 0x100
	s_addc_u32 s69, s69, 0
	s_add_u32 s85, s85, 0x100
	s_addc_u32 s86, s86, 0
	s_cmp_gt_u32 s87, 29
	s_cbranch_scc0 .LBB0_795
	s_and_b64 vcc, exec, s[12:13]
	s_cbranch_vccz .LBB0_798
	s_barrier

.LBB0_819:
	s_add_i32 s93, s60, 2
	s_add_u32 s46, s72, 0x80
	s_addc_u32 s47, s73, 0
	s_add_i32 s48, 0, 0x10000
	s_cmp_eq_u32 s87, s60
	s_cselect_b32 s61, s23, s47
	s_cselect_b32 s60, s64, s46
	s_cselect_b32 s47, s21, s92
	s_cselect_b32 s46, s90, s91
	s_add_i32 s49, 0, 0x14000
	v_add_u32_e32 v142, s48, v205
	v_add_u32_e32 v182, s49, v205
	ds_read_b128 v[130:133], v142
	ds_read_b128 v[134:137], v142 offset:1024
	ds_read_b128 v[138:141], v142 offset:2048
	ds_read_b128 v[142:145], v142 offset:3072
	ds_read_b128 v[146:149], v182
	ds_read_b128 v[150:153], v182 offset:1024
	ds_read_b128 v[178:181], v182 offset:2048
	ds_read_b128 v[182:185], v182 offset:3072
	v_lshl_add_u64 v[236:237], s[72:73], 0, v[162:163]
	s_add_i32 m0, s71, 0xc000
	ds_read_b128 v[186:189], v207
	ds_read_b128 v[208:211], v207 offset:1024
	ds_read_b128 v[212:215], v207 offset:2048
	ds_read_b128 v[216:219], v207 offset:3072
	ds_read_b128 v[220:223], v207 offset:4096
	ds_read_b128 v[224:227], v207 offset:5120
	ds_read_b128 v[228:231], v207 offset:6144
	ds_read_b128 v[232:235], v207 offset:7168
	global_load_lds_dwordx4 v[236:237], off
	v_lshl_add_u64 v[236:237], s[72:73], 0, v[164:165]
	s_add_i32 m0, s71, 0xe000
	s_nop 0
	global_load_lds_dwordx4 v[236:237], off
	s_waitcnt vmcnt(8)
	s_waitcnt lgkmcnt(0)
	s_setprio 1
	s_waitcnt lgkmcnt(0)
	v_mfma_f32_16x16x32_bf16 v[126:129], v[130:133], v[186:189], v[126:129]
	v_mfma_f32_16x16x32_bf16 v[122:125], v[138:141], v[186:189], v[122:125]
	v_mfma_f32_16x16x32_bf16 v[118:121], v[130:133], v[212:215], v[118:121]
	v_mfma_f32_16x16x32_bf16 v[114:117], v[138:141], v[212:215], v[114:117]
	s_barrier
	v_mfma_f32_16x16x32_bf16 v[110:113], v[130:133], v[220:223], v[110:113]
	v_mfma_f32_16x16x32_bf16 v[106:109], v[138:141], v[220:223], v[106:109]
	v_mfma_f32_16x16x32_bf16 v[102:105], v[130:133], v[228:231], v[102:105]
	v_mfma_f32_16x16x32_bf16 v[98:101], v[138:141], v[228:231], v[98:101]
	v_mfma_f32_16x16x32_bf16 v[126:129], v[134:137], v[208:211], v[126:129]
	v_mfma_f32_16x16x32_bf16 v[122:125], v[142:145], v[208:211], v[122:125]
	v_mfma_f32_16x16x32_bf16 v[118:121], v[134:137], v[216:219], v[118:121]
	v_mfma_f32_16x16x32_bf16 v[114:117], v[142:145], v[216:219], v[114:117]
	v_mfma_f32_16x16x32_bf16 v[110:113], v[134:137], v[224:227], v[110:113]
	v_mfma_f32_16x16x32_bf16 v[106:109], v[142:145], v[224:227], v[106:109]
	v_mfma_f32_16x16x32_bf16 v[102:105], v[134:137], v[232:235], v[102:105]
	v_mfma_f32_16x16x32_bf16 v[98:101], v[142:145], v[232:235], v[98:101]
	s_setprio 0
	s_setprio 1
	v_mfma_f32_16x16x32_bf16 v[94:97], v[146:149], v[186:189], v[94:97]
	v_mfma_f32_16x16x32_bf16 v[90:93], v[178:181], v[186:189], v[90:93]
	v_mfma_f32_16x16x32_bf16 v[86:89], v[146:149], v[212:215], v[86:89]
	v_mfma_f32_16x16x32_bf16 v[82:85], v[178:181], v[212:215], v[82:85]
	v_mfma_f32_16x16x32_bf16 v[78:81], v[146:149], v[220:223], v[78:81]
	v_mfma_f32_16x16x32_bf16 v[74:77], v[178:181], v[220:223], v[74:77]
	v_mfma_f32_16x16x32_bf16 v[70:73], v[146:149], v[228:231], v[70:73]
	v_mfma_f32_16x16x32_bf16 v[66:69], v[178:181], v[228:231], v[66:69]
	v_mfma_f32_16x16x32_bf16 v[94:97], v[150:153], v[208:211], v[94:97]
	v_mfma_f32_16x16x32_bf16 v[90:93], v[182:185], v[208:211], v[90:93]
	v_mfma_f32_16x16x32_bf16 v[86:89], v[150:153], v[216:219], v[86:89]
	v_mfma_f32_16x16x32_bf16 v[82:85], v[182:185], v[216:219], v[82:85]
	v_mfma_f32_16x16x32_bf16 v[78:81], v[150:153], v[224:227], v[78:81]
	v_mfma_f32_16x16x32_bf16 v[74:77], v[182:185], v[224:227], v[74:77]
	v_mfma_f32_16x16x32_bf16 v[70:73], v[150:153], v[232:235], v[70:73]
	v_mfma_f32_16x16x32_bf16 v[66:69], v[182:185], v[232:235], v[66:69]
	s_setprio 0
	s_barrier
	s_add_i32 s48, s48, s80
	v_lshl_add_u64 v[236:237], s[46:47], 0, v[166:167]
	s_mov_b32 m0, s48
	ds_read_b128 v[186:189], v207 offset:16384
	ds_read_b128 v[208:211], v207 offset:17408
	ds_read_b128 v[212:215], v207 offset:18432
	ds_read_b128 v[216:219], v207 offset:19456
	ds_read_b128 v[220:223], v207 offset:20480
	ds_read_b128 v[224:227], v207 offset:21504
	ds_read_b128 v[228:231], v207 offset:22528
	ds_read_b128 v[232:235], v207 offset:23552
	global_load_lds_dwordx4 v[236:237], off
	s_add_i32 m0, s48, 0x2000
	v_lshl_add_u64 v[242:243], s[46:47], 0, v[158:159]
	s_add_u32 s46, s46, s26
	s_addc_u32 s47, s47, 0
	s_add_i32 s48, s49, s80
	global_load_lds_dwordx4 v[242:243], off
	v_lshl_add_u64 v[244:245], s[46:47], 0, v[166:167]
	s_mov_b32 m0, s48
	v_lshl_add_u64 v[246:247], s[46:47], 0, v[158:159]
	global_load_lds_dwordx4 v[244:245], off
	s_add_i32 m0, s48, 0x2000
	v_lshl_add_u64 v[248:249], s[60:61], 0, v[154:155]
	global_load_lds_dwordx4 v[246:247], off
	s_mov_b32 m0, s71
	v_lshl_add_u64 v[250:251], s[60:61], 0, v[156:157]
	global_load_lds_dwordx4 v[248:249], off
	s_mov_b32 m0, s81
	s_nop 0
	global_load_lds_dwordx4 v[250:251], off
	s_waitcnt vmcnt(8)
	s_waitcnt lgkmcnt(0)
	s_setprio 1
	s_waitcnt lgkmcnt(0)
	v_mfma_f32_16x16x32_bf16 v[62:65], v[130:133], v[186:189], v[62:65]
	v_mfma_f32_16x16x32_bf16 v[58:61], v[138:141], v[186:189], v[58:61]
	v_mfma_f32_16x16x32_bf16 v[54:57], v[130:133], v[212:215], v[54:57]
	v_mfma_f32_16x16x32_bf16 v[50:53], v[138:141], v[212:215], v[50:53]
	s_barrier
	v_mfma_f32_16x16x32_bf16 v[46:49], v[130:133], v[220:223], v[46:49]
	v_mfma_f32_16x16x32_bf16 v[42:45], v[138:141], v[220:223], v[42:45]
	v_mfma_f32_16x16x32_bf16 v[38:41], v[130:133], v[228:231], v[38:41]
	v_mfma_f32_16x16x32_bf16 v[34:37], v[138:141], v[228:231], v[34:37]
	v_mfma_f32_16x16x32_bf16 v[62:65], v[134:137], v[208:211], v[62:65]
	v_mfma_f32_16x16x32_bf16 v[58:61], v[142:145], v[208:211], v[58:61]
	v_mfma_f32_16x16x32_bf16 v[54:57], v[134:137], v[216:219], v[54:57]
	v_mfma_f32_16x16x32_bf16 v[50:53], v[142:145], v[216:219], v[50:53]
	v_mfma_f32_16x16x32_bf16 v[46:49], v[134:137], v[224:227], v[46:49]
	v_mfma_f32_16x16x32_bf16 v[42:45], v[142:145], v[224:227], v[42:45]
	v_mfma_f32_16x16x32_bf16 v[38:41], v[134:137], v[232:235], v[38:41]
	v_mfma_f32_16x16x32_bf16 v[34:37], v[142:145], v[232:235], v[34:37]
	s_setprio 0
	s_setprio 1
	v_mfma_f32_16x16x32_bf16 v[30:33], v[146:149], v[186:189], v[30:33]
	v_mfma_f32_16x16x32_bf16 v[26:29], v[178:181], v[186:189], v[26:29]
	v_mfma_f32_16x16x32_bf16 v[22:25], v[146:149], v[212:215], v[22:25]
	v_mfma_f32_16x16x32_bf16 v[18:21], v[178:181], v[212:215], v[18:21]
	v_mfma_f32_16x16x32_bf16 v[14:17], v[146:149], v[220:223], v[14:17]
	v_mfma_f32_16x16x32_bf16 v[10:13], v[178:181], v[220:223], v[10:13]
	v_mfma_f32_16x16x32_bf16 v[6:9], v[146:149], v[228:231], v[6:9]
	v_mfma_f32_16x16x32_bf16 v[2:5], v[178:181], v[228:231], v[2:5]
	v_mfma_f32_16x16x32_bf16 v[30:33], v[150:153], v[208:211], v[30:33]
	v_mfma_f32_16x16x32_bf16 v[26:29], v[182:185], v[208:211], v[26:29]
	v_mfma_f32_16x16x32_bf16 v[22:25], v[150:153], v[216:219], v[22:25]
	v_mfma_f32_16x16x32_bf16 v[18:21], v[182:185], v[216:219], v[18:21]
	v_mfma_f32_16x16x32_bf16 v[14:17], v[150:153], v[224:227], v[14:17]
	v_mfma_f32_16x16x32_bf16 v[10:13], v[182:185], v[224:227], v[10:13]
	v_mfma_f32_16x16x32_bf16 v[6:9], v[150:153], v[232:235], v[6:9]
	v_mfma_f32_16x16x32_bf16 v[2:5], v[182:185], v[232:235], v[2:5]
	s_setprio 0
	s_barrier
	s_add_i32 s48, 0, 0x18000
	s_add_i32 s49, 0, 0x1c000
	v_add_u32_e32 v142, s48, v205
	v_add_u32_e32 v182, s49, v205
	ds_read_b128 v[130:133], v142
	ds_read_b128 v[134:137], v142 offset:1024
	ds_read_b128 v[138:141], v142 offset:2048
	ds_read_b128 v[142:145], v142 offset:3072
	ds_read_b128 v[146:149], v182
	ds_read_b128 v[150:153], v182 offset:1024
	ds_read_b128 v[178:181], v182 offset:2048
	ds_read_b128 v[182:185], v182 offset:3072
	s_add_u32 s46, s60, s26
	s_addc_u32 s47, s61, 0
	s_mov_b32 m0, s82
	v_lshl_add_u64 v[252:253], s[46:47], 0, v[154:155]
	ds_read_b128 v[186:189], v207 offset:32768
	ds_read_b128 v[208:211], v207 offset:33792
	ds_read_b128 v[212:215], v207 offset:34816
	ds_read_b128 v[216:219], v207 offset:35840
	ds_read_b128 v[220:223], v207 offset:36864
	ds_read_b128 v[224:227], v207 offset:37888
	ds_read_b128 v[228:231], v207 offset:38912
	ds_read_b128 v[232:235], v207 offset:39936
	global_load_lds_dwordx4 v[252:253], off
	v_lshl_add_u64 v[252:253], s[46:47], 0, v[156:157]
	s_mov_b32 m0, s83
	s_nop 0
	global_load_lds_dwordx4 v[252:253], off
	s_waitcnt vmcnt(8)
	s_waitcnt lgkmcnt(0)
	s_setprio 1
	s_waitcnt lgkmcnt(0)
	v_mfma_f32_16x16x32_bf16 v[126:129], v[130:133], v[186:189], v[126:129]
	v_mfma_f32_16x16x32_bf16 v[122:125], v[138:141], v[186:189], v[122:125]
	v_mfma_f32_16x16x32_bf16 v[118:121], v[130:133], v[212:215], v[118:121]
	v_mfma_f32_16x16x32_bf16 v[114:117], v[138:141], v[212:215], v[114:117]
	s_barrier
	v_mfma_f32_16x16x32_bf16 v[110:113], v[130:133], v[220:223], v[110:113]
	v_mfma_f32_16x16x32_bf16 v[106:109], v[138:141], v[220:223], v[106:109]
	v_mfma_f32_16x16x32_bf16 v[102:105], v[130:133], v[228:231], v[102:105]
	v_mfma_f32_16x16x32_bf16 v[98:101], v[138:141], v[228:231], v[98:101]
	v_mfma_f32_16x16x32_bf16 v[126:129], v[134:137], v[208:211], v[126:129]
	v_mfma_f32_16x16x32_bf16 v[122:125], v[142:145], v[208:211], v[122:125]
	v_mfma_f32_16x16x32_bf16 v[118:121], v[134:137], v[216:219], v[118:121]
	v_mfma_f32_16x16x32_bf16 v[114:117], v[142:145], v[216:219], v[114:117]
	v_mfma_f32_16x16x32_bf16 v[110:113], v[134:137], v[224:227], v[110:113]
	v_mfma_f32_16x16x32_bf16 v[106:109], v[142:145], v[224:227], v[106:109]
	v_mfma_f32_16x16x32_bf16 v[102:105], v[134:137], v[232:235], v[102:105]
	v_mfma_f32_16x16x32_bf16 v[98:101], v[142:145], v[232:235], v[98:101]
	s_setprio 0
	s_setprio 1
	v_mfma_f32_16x16x32_bf16 v[94:97], v[146:149], v[186:189], v[94:97]
	v_mfma_f32_16x16x32_bf16 v[90:93], v[178:181], v[186:189], v[90:93]
	v_mfma_f32_16x16x32_bf16 v[86:89], v[146:149], v[212:215], v[86:89]
	v_mfma_f32_16x16x32_bf16 v[82:85], v[178:181], v[212:215], v[82:85]
	v_mfma_f32_16x16x32_bf16 v[78:81], v[146:149], v[220:223], v[78:81]
	v_mfma_f32_16x16x32_bf16 v[74:77], v[178:181], v[220:223], v[74:77]
	v_mfma_f32_16x16x32_bf16 v[70:73], v[146:149], v[228:231], v[70:73]
	v_mfma_f32_16x16x32_bf16 v[66:69], v[178:181], v[228:231], v[66:69]
	v_mfma_f32_16x16x32_bf16 v[94:97], v[150:153], v[208:211], v[94:97]
	v_mfma_f32_16x16x32_bf16 v[90:93], v[182:185], v[208:211], v[90:93]
	v_mfma_f32_16x16x32_bf16 v[86:89], v[150:153], v[216:219], v[86:89]
	v_mfma_f32_16x16x32_bf16 v[82:85], v[182:185], v[216:219], v[82:85]
	v_mfma_f32_16x16x32_bf16 v[78:81], v[150:153], v[224:227], v[78:81]
	v_mfma_f32_16x16x32_bf16 v[74:77], v[182:185], v[224:227], v[74:77]
	v_mfma_f32_16x16x32_bf16 v[70:73], v[150:153], v[232:235], v[70:73]
	v_mfma_f32_16x16x32_bf16 v[66:69], v[182:185], v[232:235], v[66:69]
	s_setprio 0
	s_barrier
	s_add_i32 s46, s48, s80
	v_lshl_add_u64 v[236:237], v[236:237], 0, s[42:43]
	s_mov_b32 m0, s46
	ds_read_b128 v[186:189], v207 offset:49152
	ds_read_b128 v[208:211], v207 offset:50176
	ds_read_b128 v[212:215], v207 offset:51200
	ds_read_b128 v[216:219], v207 offset:52224
	ds_read_b128 v[220:223], v207 offset:53248
	ds_read_b128 v[224:227], v207 offset:54272
	ds_read_b128 v[228:231], v207 offset:55296
	ds_read_b128 v[232:235], v207 offset:56320
	global_load_lds_dwordx4 v[236:237], off
	v_lshl_add_u64 v[236:237], v[242:243], 0, s[42:43]
	s_add_i32 m0, s46, 0x2000
	s_add_i32 s46, s49, s80
	global_load_lds_dwordx4 v[236:237], off
	v_lshl_add_u64 v[236:237], v[244:245], 0, s[42:43]
	s_mov_b32 m0, s46
	s_nop 0
	global_load_lds_dwordx4 v[236:237], off
	v_lshl_add_u64 v[236:237], v[246:247], 0, s[42:43]
	s_add_i32 m0, s46, 0x2000
	s_nop 0
	global_load_lds_dwordx4 v[236:237], off
	v_lshl_add_u64 v[236:237], v[248:249], 0, s[42:43]
	s_mov_b32 m0, s85
	s_nop 0
	global_load_lds_dwordx4 v[236:237], off
	v_lshl_add_u64 v[236:237], v[250:251], 0, s[42:43]
	s_mov_b32 m0, s86
	s_nop 0
	global_load_lds_dwordx4 v[236:237], off
	s_waitcnt vmcnt(8)
	s_waitcnt lgkmcnt(0)
	s_setprio 1
	s_waitcnt lgkmcnt(0)
	v_mfma_f32_16x16x32_bf16 v[62:65], v[130:133], v[186:189], v[62:65]
	v_mfma_f32_16x16x32_bf16 v[58:61], v[138:141], v[186:189], v[58:61]
	v_mfma_f32_16x16x32_bf16 v[54:57], v[130:133], v[212:215], v[54:57]
	v_mfma_f32_16x16x32_bf16 v[50:53], v[138:141], v[212:215], v[50:53]
	s_barrier
	v_mfma_f32_16x16x32_bf16 v[46:49], v[130:133], v[220:223], v[46:49]
	v_mfma_f32_16x16x32_bf16 v[42:45], v[138:141], v[220:223], v[42:45]
	v_mfma_f32_16x16x32_bf16 v[38:41], v[130:133], v[228:231], v[38:41]
	v_mfma_f32_16x16x32_bf16 v[34:37], v[138:141], v[228:231], v[34:37]
	v_mfma_f32_16x16x32_bf16 v[62:65], v[134:137], v[208:211], v[62:65]
	v_mfma_f32_16x16x32_bf16 v[58:61], v[142:145], v[208:211], v[58:61]
	v_mfma_f32_16x16x32_bf16 v[54:57], v[134:137], v[216:219], v[54:57]
	v_mfma_f32_16x16x32_bf16 v[50:53], v[142:145], v[216:219], v[50:53]
	v_mfma_f32_16x16x32_bf16 v[46:49], v[134:137], v[224:227], v[46:49]
	v_mfma_f32_16x16x32_bf16 v[42:45], v[142:145], v[224:227], v[42:45]
	v_mfma_f32_16x16x32_bf16 v[38:41], v[134:137], v[232:235], v[38:41]
	v_mfma_f32_16x16x32_bf16 v[34:37], v[142:145], v[232:235], v[34:37]
	s_setprio 0
	s_setprio 1
	v_mfma_f32_16x16x32_bf16 v[30:33], v[146:149], v[186:189], v[30:33]
	v_mfma_f32_16x16x32_bf16 v[26:29], v[178:181], v[186:189], v[26:29]
	v_mfma_f32_16x16x32_bf16 v[22:25], v[146:149], v[212:215], v[22:25]
	v_mfma_f32_16x16x32_bf16 v[18:21], v[178:181], v[212:215], v[18:21]
	v_mfma_f32_16x16x32_bf16 v[14:17], v[146:149], v[220:223], v[14:17]
	v_mfma_f32_16x16x32_bf16 v[10:13], v[178:181], v[220:223], v[10:13]
	v_mfma_f32_16x16x32_bf16 v[6:9], v[146:149], v[228:231], v[6:9]
	v_mfma_f32_16x16x32_bf16 v[2:5], v[178:181], v[228:231], v[2:5]
	v_mfma_f32_16x16x32_bf16 v[30:33], v[150:153], v[208:211], v[30:33]
	v_mfma_f32_16x16x32_bf16 v[26:29], v[182:185], v[208:211], v[26:29]
	v_mfma_f32_16x16x32_bf16 v[22:25], v[150:153], v[216:219], v[22:25]
	v_mfma_f32_16x16x32_bf16 v[18:21], v[182:185], v[216:219], v[18:21]
	v_mfma_f32_16x16x32_bf16 v[14:17], v[150:153], v[224:227], v[14:17]
	v_mfma_f32_16x16x32_bf16 v[10:13], v[182:185], v[224:227], v[10:13]
	v_mfma_f32_16x16x32_bf16 v[6:9], v[150:153], v[232:235], v[6:9]
	v_mfma_f32_16x16x32_bf16 v[2:5], v[182:185], v[232:235], v[2:5]
	s_setprio 0
	s_barrier
	s_add_u32 s72, s72, 0x100
	s_addc_u32 s73, s73, 0
	s_add_u32 s91, s91, 0x100
	s_addc_u32 s92, s92, 0
	s_cmp_ge_u32 s93, s84
	s_mov_b32 s60, s93
	s_cbranch_scc0 .LBB0_819
	s_and_b64 vcc, exec, s[18:19]
	s_cbranch_vccz .LBB0_822
	s_barrier

.LBB0_903:
	s_add_u32 s46, s66, 0xfff80080
	s_addc_u32 s47, s67, -1
	s_add_i32 s48, 0, 0x10000
	s_cmp_eq_u32 s84, 28
	s_cselect_b32 s69, s17, s47
	s_cselect_b32 s68, s64, s46
	s_cselect_b32 s61, s13, s83
	s_cselect_b32 s60, s81, s82
	s_add_i32 s49, 0, 0x14000
	v_add_u32_e32 v142, s48, v186
	v_add_u32_e32 v164, s49, v186
	ds_read_b128 v[130:133], v142
	ds_read_b128 v[134:137], v142 offset:1024
	ds_read_b128 v[138:141], v142 offset:2048
	ds_read_b128 v[142:145], v142 offset:3072
	ds_read_b128 v[146:149], v164
	ds_read_b128 v[160:163], v164 offset:1024
	ds_read_b128 v[178:181], v164 offset:2048
	ds_read_b128 v[182:185], v164 offset:3072
	v_lshl_add_u64 v[164:165], s[66:67], 0, v[156:157]
	s_add_i32 m0, s74, 0xc000
	ds_read_b128 v[206:209], v188
	ds_read_b128 v[210:213], v188 offset:1024
	ds_read_b128 v[214:217], v188 offset:2048
	ds_read_b128 v[218:221], v188 offset:3072
	ds_read_b128 v[222:225], v188 offset:4096
	ds_read_b128 v[226:229], v188 offset:5120
	ds_read_b128 v[230:233], v188 offset:6144
	ds_read_b128 v[234:237], v188 offset:7168
	global_load_lds_dwordx4 v[164:165], off
	v_lshl_add_u64 v[164:165], s[66:67], 0, v[158:159]
	s_add_i32 m0, s74, 0xe000
	s_nop 0
	global_load_lds_dwordx4 v[164:165], off
	s_waitcnt vmcnt(8)
	s_waitcnt lgkmcnt(0)
	s_setprio 1
	s_waitcnt lgkmcnt(0)
	v_mfma_f32_16x16x32_bf16 v[126:129], v[130:133], v[206:209], v[126:129]
	v_mfma_f32_16x16x32_bf16 v[122:125], v[138:141], v[206:209], v[122:125]
	v_mfma_f32_16x16x32_bf16 v[118:121], v[130:133], v[214:217], v[118:121]
	v_mfma_f32_16x16x32_bf16 v[110:113], v[138:141], v[214:217], v[110:113]
	s_barrier
	v_mfma_f32_16x16x32_bf16 v[94:97], v[130:133], v[222:225], v[94:97]
	v_mfma_f32_16x16x32_bf16 v[90:93], v[138:141], v[222:225], v[90:93]
	v_mfma_f32_16x16x32_bf16 v[82:85], v[130:133], v[230:233], v[82:85]
	v_mfma_f32_16x16x32_bf16 v[74:77], v[138:141], v[230:233], v[74:77]
	v_mfma_f32_16x16x32_bf16 v[126:129], v[134:137], v[210:213], v[126:129]
	v_mfma_f32_16x16x32_bf16 v[122:125], v[142:145], v[210:213], v[122:125]
	v_mfma_f32_16x16x32_bf16 v[118:121], v[134:137], v[218:221], v[118:121]
	v_mfma_f32_16x16x32_bf16 v[110:113], v[142:145], v[218:221], v[110:113]
	v_mfma_f32_16x16x32_bf16 v[94:97], v[134:137], v[226:229], v[94:97]
	v_mfma_f32_16x16x32_bf16 v[90:93], v[142:145], v[226:229], v[90:93]
	v_mfma_f32_16x16x32_bf16 v[82:85], v[134:137], v[234:237], v[82:85]
	v_mfma_f32_16x16x32_bf16 v[74:77], v[142:145], v[234:237], v[74:77]
	s_setprio 0
	s_setprio 1
	v_mfma_f32_16x16x32_bf16 v[114:117], v[146:149], v[206:209], v[114:117]
	v_mfma_f32_16x16x32_bf16 v[106:109], v[178:181], v[206:209], v[106:109]
	v_mfma_f32_16x16x32_bf16 v[102:105], v[146:149], v[214:217], v[102:105]
	v_mfma_f32_16x16x32_bf16 v[98:101], v[178:181], v[214:217], v[98:101]
	v_mfma_f32_16x16x32_bf16 v[86:89], v[146:149], v[222:225], v[86:89]
	v_mfma_f32_16x16x32_bf16 v[78:81], v[178:181], v[222:225], v[78:81]
	v_mfma_f32_16x16x32_bf16 v[70:73], v[146:149], v[230:233], v[70:73]
	v_mfma_f32_16x16x32_bf16 v[66:69], v[178:181], v[230:233], v[66:69]
	v_mfma_f32_16x16x32_bf16 v[114:117], v[160:163], v[210:213], v[114:117]
	v_mfma_f32_16x16x32_bf16 v[106:109], v[182:185], v[210:213], v[106:109]
	v_mfma_f32_16x16x32_bf16 v[102:105], v[160:163], v[218:221], v[102:105]
	v_mfma_f32_16x16x32_bf16 v[98:101], v[182:185], v[218:221], v[98:101]
	v_mfma_f32_16x16x32_bf16 v[86:89], v[160:163], v[226:229], v[86:89]
	v_mfma_f32_16x16x32_bf16 v[78:81], v[182:185], v[226:229], v[78:81]
	v_mfma_f32_16x16x32_bf16 v[70:73], v[160:163], v[234:237], v[70:73]
	v_mfma_f32_16x16x32_bf16 v[66:69], v[182:185], v[234:237], v[66:69]
	s_setprio 0
	s_barrier
	s_add_i32 s46, s48, s73
	v_lshl_add_u64 v[164:165], s[60:61], 0, v[166:167]
	s_mov_b32 m0, s46
	ds_read_b128 v[206:209], v188 offset:16384
	ds_read_b128 v[210:213], v188 offset:17408
	ds_read_b128 v[214:217], v188 offset:18432
	ds_read_b128 v[218:221], v188 offset:19456
	ds_read_b128 v[222:225], v188 offset:20480
	ds_read_b128 v[226:229], v188 offset:21504
	ds_read_b128 v[230:233], v188 offset:22528
	ds_read_b128 v[234:237], v188 offset:23552
	global_load_lds_dwordx4 v[164:165], off
	s_add_i32 m0, s46, 0x2000
	s_add_u32 s46, s60, 0x80000
	v_lshl_add_u64 v[242:243], s[60:61], 0, v[154:155]
	s_addc_u32 s47, s61, 0
	s_add_i32 s48, s49, s73
	global_load_lds_dwordx4 v[242:243], off
	v_lshl_add_u64 v[244:245], s[46:47], 0, v[166:167]
	s_mov_b32 m0, s48
	v_lshl_add_u64 v[246:247], s[68:69], 0, v[152:153]
	global_load_lds_dwordx4 v[244:245], off
	v_lshl_add_u64 v[244:245], s[46:47], 0, v[154:155]
	s_add_i32 m0, s48, 0x2000
	s_nop 0
	global_load_lds_dwordx4 v[244:245], off
	v_lshl_add_u64 v[244:245], s[68:69], 0, v[150:151]
	s_mov_b32 m0, s74
	s_nop 0
	global_load_lds_dwordx4 v[244:245], off
	s_mov_b32 m0, s75
	s_nop 0
	global_load_lds_dwordx4 v[246:247], off
	s_waitcnt vmcnt(8)
	s_waitcnt lgkmcnt(0)
	s_setprio 1
	s_waitcnt lgkmcnt(0)
	v_mfma_f32_16x16x32_bf16 v[62:65], v[130:133], v[206:209], v[62:65]
	v_mfma_f32_16x16x32_bf16 v[58:61], v[138:141], v[206:209], v[58:61]
	v_mfma_f32_16x16x32_bf16 v[50:53], v[130:133], v[214:217], v[50:53]
	v_mfma_f32_16x16x32_bf16 v[42:45], v[138:141], v[214:217], v[42:45]
	s_barrier
	v_mfma_f32_16x16x32_bf16 v[34:37], v[130:133], v[222:225], v[34:37]
	v_mfma_f32_16x16x32_bf16 v[26:29], v[138:141], v[222:225], v[26:29]
	v_mfma_f32_16x16x32_bf16 v[18:21], v[130:133], v[230:233], v[18:21]
	v_mfma_f32_16x16x32_bf16 v[10:13], v[138:141], v[230:233], v[10:13]
	v_mfma_f32_16x16x32_bf16 v[62:65], v[134:137], v[210:213], v[62:65]
	v_mfma_f32_16x16x32_bf16 v[58:61], v[142:145], v[210:213], v[58:61]
	v_mfma_f32_16x16x32_bf16 v[50:53], v[134:137], v[218:221], v[50:53]
	v_mfma_f32_16x16x32_bf16 v[42:45], v[142:145], v[218:221], v[42:45]
	v_mfma_f32_16x16x32_bf16 v[34:37], v[134:137], v[226:229], v[34:37]
	v_mfma_f32_16x16x32_bf16 v[26:29], v[142:145], v[226:229], v[26:29]
	v_mfma_f32_16x16x32_bf16 v[18:21], v[134:137], v[234:237], v[18:21]
	v_mfma_f32_16x16x32_bf16 v[10:13], v[142:145], v[234:237], v[10:13]
	s_setprio 0
	s_setprio 1
	v_mfma_f32_16x16x32_bf16 v[54:57], v[146:149], v[206:209], v[54:57]
	v_mfma_f32_16x16x32_bf16 v[46:49], v[178:181], v[206:209], v[46:49]
	v_mfma_f32_16x16x32_bf16 v[38:41], v[146:149], v[214:217], v[38:41]
	v_mfma_f32_16x16x32_bf16 v[30:33], v[178:181], v[214:217], v[30:33]
	v_mfma_f32_16x16x32_bf16 v[22:25], v[146:149], v[222:225], v[22:25]
	v_mfma_f32_16x16x32_bf16 v[14:17], v[178:181], v[222:225], v[14:17]
	v_mfma_f32_16x16x32_bf16 v[6:9], v[146:149], v[230:233], v[6:9]
	v_mfma_f32_16x16x32_bf16 v[2:5], v[178:181], v[230:233], v[2:5]
	v_mfma_f32_16x16x32_bf16 v[54:57], v[160:163], v[210:213], v[54:57]
	v_mfma_f32_16x16x32_bf16 v[46:49], v[182:185], v[210:213], v[46:49]
	v_mfma_f32_16x16x32_bf16 v[38:41], v[160:163], v[218:221], v[38:41]
	v_mfma_f32_16x16x32_bf16 v[30:33], v[182:185], v[218:221], v[30:33]
	v_mfma_f32_16x16x32_bf16 v[22:25], v[160:163], v[226:229], v[22:25]
	v_mfma_f32_16x16x32_bf16 v[14:17], v[182:185], v[226:229], v[14:17]
	v_mfma_f32_16x16x32_bf16 v[6:9], v[160:163], v[234:237], v[6:9]
	v_mfma_f32_16x16x32_bf16 v[2:5], v[182:185], v[234:237], v[2:5]
	s_setprio 0
	s_barrier
	s_add_i32 s48, 0, 0x18000
	s_add_i32 s49, 0, 0x1c000
	v_add_u32_e32 v142, s48, v186
	v_add_u32_e32 v182, s49, v186
	ds_read_b128 v[130:133], v142
	ds_read_b128 v[134:137], v142 offset:1024
	ds_read_b128 v[138:141], v142 offset:2048
	ds_read_b128 v[142:145], v142 offset:3072
	ds_read_b128 v[146:149], v182
	ds_read_b128 v[160:163], v182 offset:1024
	ds_read_b128 v[178:181], v182 offset:2048
	ds_read_b128 v[182:185], v182 offset:3072
	s_add_u32 s46, s68, 0x80000
	s_addc_u32 s47, s69, 0
	s_mov_b32 m0, s76
	v_lshl_add_u64 v[248:249], s[46:47], 0, v[150:151]
	ds_read_b128 v[206:209], v188 offset:32768
	ds_read_b128 v[210:213], v188 offset:33792
	ds_read_b128 v[214:217], v188 offset:34816
	ds_read_b128 v[218:221], v188 offset:35840
	ds_read_b128 v[222:225], v188 offset:36864
	ds_read_b128 v[226:229], v188 offset:37888
	ds_read_b128 v[230:233], v188 offset:38912
	ds_read_b128 v[234:237], v188 offset:39936
	global_load_lds_dwordx4 v[248:249], off
	v_lshl_add_u64 v[248:249], s[46:47], 0, v[152:153]
	s_mov_b32 m0, s77
	s_nop 0
	global_load_lds_dwordx4 v[248:249], off
	s_waitcnt vmcnt(8)
	s_waitcnt lgkmcnt(0)
	s_setprio 1
	s_waitcnt lgkmcnt(0)
	v_mfma_f32_16x16x32_bf16 v[126:129], v[130:133], v[206:209], v[126:129]
	v_mfma_f32_16x16x32_bf16 v[122:125], v[138:141], v[206:209], v[122:125]
	v_mfma_f32_16x16x32_bf16 v[118:121], v[130:133], v[214:217], v[118:121]
	v_mfma_f32_16x16x32_bf16 v[110:113], v[138:141], v[214:217], v[110:113]
	s_barrier
	v_mfma_f32_16x16x32_bf16 v[94:97], v[130:133], v[222:225], v[94:97]
	v_mfma_f32_16x16x32_bf16 v[90:93], v[138:141], v[222:225], v[90:93]
	v_mfma_f32_16x16x32_bf16 v[82:85], v[130:133], v[230:233], v[82:85]
	v_mfma_f32_16x16x32_bf16 v[74:77], v[138:141], v[230:233], v[74:77]
	v_mfma_f32_16x16x32_bf16 v[126:129], v[134:137], v[210:213], v[126:129]
	v_mfma_f32_16x16x32_bf16 v[122:125], v[142:145], v[210:213], v[122:125]
	v_mfma_f32_16x16x32_bf16 v[118:121], v[134:137], v[218:221], v[118:121]
	v_mfma_f32_16x16x32_bf16 v[110:113], v[142:145], v[218:221], v[110:113]
	v_mfma_f32_16x16x32_bf16 v[94:97], v[134:137], v[226:229], v[94:97]
	v_mfma_f32_16x16x32_bf16 v[90:93], v[142:145], v[226:229], v[90:93]
	v_mfma_f32_16x16x32_bf16 v[82:85], v[134:137], v[234:237], v[82:85]
	v_mfma_f32_16x16x32_bf16 v[74:77], v[142:145], v[234:237], v[74:77]
	s_setprio 0
	s_setprio 1
	v_mfma_f32_16x16x32_bf16 v[114:117], v[146:149], v[206:209], v[114:117]
	v_mfma_f32_16x16x32_bf16 v[106:109], v[178:181], v[206:209], v[106:109]
	v_mfma_f32_16x16x32_bf16 v[102:105], v[146:149], v[214:217], v[102:105]
	v_mfma_f32_16x16x32_bf16 v[98:101], v[178:181], v[214:217], v[98:101]
	v_mfma_f32_16x16x32_bf16 v[86:89], v[146:149], v[222:225], v[86:89]
	v_mfma_f32_16x16x32_bf16 v[78:81], v[178:181], v[222:225], v[78:81]
	v_mfma_f32_16x16x32_bf16 v[70:73], v[146:149], v[230:233], v[70:73]
	v_mfma_f32_16x16x32_bf16 v[66:69], v[178:181], v[230:233], v[66:69]
	v_mfma_f32_16x16x32_bf16 v[114:117], v[160:163], v[210:213], v[114:117]
	v_mfma_f32_16x16x32_bf16 v[106:109], v[182:185], v[210:213], v[106:109]
	v_mfma_f32_16x16x32_bf16 v[102:105], v[160:163], v[218:221], v[102:105]
	v_mfma_f32_16x16x32_bf16 v[98:101], v[182:185], v[218:221], v[98:101]
	v_mfma_f32_16x16x32_bf16 v[86:89], v[160:163], v[226:229], v[86:89]
	v_mfma_f32_16x16x32_bf16 v[78:81], v[182:185], v[226:229], v[78:81]
	v_mfma_f32_16x16x32_bf16 v[70:73], v[160:163], v[234:237], v[70:73]
	v_mfma_f32_16x16x32_bf16 v[66:69], v[182:185], v[234:237], v[66:69]
	s_setprio 0
	s_barrier
	s_add_i32 s46, s48, s73
	v_lshl_add_u64 v[164:165], v[164:165], 0, s[42:43]
	s_mov_b32 m0, s46
	ds_read_b128 v[206:209], v188 offset:49152
	ds_read_b128 v[210:213], v188 offset:50176
	ds_read_b128 v[214:217], v188 offset:51200
	ds_read_b128 v[218:221], v188 offset:52224
	ds_read_b128 v[222:225], v188 offset:53248
	ds_read_b128 v[226:229], v188 offset:54272
	ds_read_b128 v[230:233], v188 offset:55296
	ds_read_b128 v[234:237], v188 offset:56320
	global_load_lds_dwordx4 v[164:165], off
	s_add_i32 m0, s46, 0x2000
	s_add_u32 s46, s60, 0x80080
	v_lshl_add_u64 v[164:165], v[242:243], 0, s[42:43]
	s_addc_u32 s47, s61, 0
	s_add_i32 s48, s49, s73
	global_load_lds_dwordx4 v[164:165], off
	v_lshl_add_u64 v[164:165], s[46:47], 0, v[166:167]
	s_mov_b32 m0, s48
	s_nop 0
	global_load_lds_dwordx4 v[164:165], off
	v_lshl_add_u64 v[164:165], s[46:47], 0, v[154:155]
	s_add_i32 m0, s48, 0x2000
	s_nop 0
	global_load_lds_dwordx4 v[164:165], off
	v_lshl_add_u64 v[164:165], v[244:245], 0, s[42:43]
	s_mov_b32 m0, s78
	s_nop 0
	global_load_lds_dwordx4 v[164:165], off
	v_lshl_add_u64 v[164:165], v[246:247], 0, s[42:43]
	s_mov_b32 m0, s79
	s_nop 0
	global_load_lds_dwordx4 v[164:165], off
	s_waitcnt vmcnt(8)
	s_waitcnt lgkmcnt(0)
	s_setprio 1
	s_waitcnt lgkmcnt(0)
	v_mfma_f32_16x16x32_bf16 v[62:65], v[130:133], v[206:209], v[62:65]
	v_mfma_f32_16x16x32_bf16 v[58:61], v[138:141], v[206:209], v[58:61]
	v_mfma_f32_16x16x32_bf16 v[50:53], v[130:133], v[214:217], v[50:53]
	v_mfma_f32_16x16x32_bf16 v[42:45], v[138:141], v[214:217], v[42:45]
	s_barrier
	v_mfma_f32_16x16x32_bf16 v[34:37], v[130:133], v[222:225], v[34:37]
	v_mfma_f32_16x16x32_bf16 v[26:29], v[138:141], v[222:225], v[26:29]
	v_mfma_f32_16x16x32_bf16 v[18:21], v[130:133], v[230:233], v[18:21]
	v_mfma_f32_16x16x32_bf16 v[10:13], v[138:141], v[230:233], v[10:13]
	v_mfma_f32_16x16x32_bf16 v[62:65], v[134:137], v[210:213], v[62:65]
	v_mfma_f32_16x16x32_bf16 v[58:61], v[142:145], v[210:213], v[58:61]
	v_mfma_f32_16x16x32_bf16 v[50:53], v[134:137], v[218:221], v[50:53]
	v_mfma_f32_16x16x32_bf16 v[42:45], v[142:145], v[218:221], v[42:45]
	v_mfma_f32_16x16x32_bf16 v[34:37], v[134:137], v[226:229], v[34:37]
	v_mfma_f32_16x16x32_bf16 v[26:29], v[142:145], v[226:229], v[26:29]
	v_mfma_f32_16x16x32_bf16 v[18:21], v[134:137], v[234:237], v[18:21]
	v_mfma_f32_16x16x32_bf16 v[10:13], v[142:145], v[234:237], v[10:13]
	s_setprio 0
	s_setprio 1
	v_mfma_f32_16x16x32_bf16 v[54:57], v[146:149], v[206:209], v[54:57]
	v_mfma_f32_16x16x32_bf16 v[46:49], v[178:181], v[206:209], v[46:49]
	v_mfma_f32_16x16x32_bf16 v[38:41], v[146:149], v[214:217], v[38:41]
	v_mfma_f32_16x16x32_bf16 v[30:33], v[178:181], v[214:217], v[30:33]
	v_mfma_f32_16x16x32_bf16 v[22:25], v[146:149], v[222:225], v[22:25]
	v_mfma_f32_16x16x32_bf16 v[14:17], v[178:181], v[222:225], v[14:17]
	v_mfma_f32_16x16x32_bf16 v[6:9], v[146:149], v[230:233], v[6:9]
	v_mfma_f32_16x16x32_bf16 v[2:5], v[178:181], v[230:233], v[2:5]
	v_mfma_f32_16x16x32_bf16 v[54:57], v[160:163], v[210:213], v[54:57]
	v_mfma_f32_16x16x32_bf16 v[46:49], v[182:185], v[210:213], v[46:49]
	v_mfma_f32_16x16x32_bf16 v[38:41], v[160:163], v[218:221], v[38:41]
	v_mfma_f32_16x16x32_bf16 v[30:33], v[182:185], v[218:221], v[30:33]
	v_mfma_f32_16x16x32_bf16 v[22:25], v[160:163], v[226:229], v[22:25]
	v_mfma_f32_16x16x32_bf16 v[14:17], v[182:185], v[226:229], v[14:17]
	v_mfma_f32_16x16x32_bf16 v[6:9], v[160:163], v[234:237], v[6:9]
	v_mfma_f32_16x16x32_bf16 v[2:5], v[182:185], v[234:237], v[2:5]
	s_setprio 0
	s_barrier
	s_add_i32 s84, s84, 2
	s_add_u32 s66, s66, 0x100
	s_addc_u32 s67, s67, 0
	s_add_u32 s82, s82, 0x100
	s_addc_u32 s83, s83, 0
	s_cmp_gt_u32 s84, 29
	s_cbranch_scc0 .LBB0_903
	s_and_b64 vcc, exec, s[10:11]
	s_cbranch_vccz .LBB0_906
	s_barrier

.LBB0_1035:
	s_add_u32 s46, s64, 0xfff80080
	s_addc_u32 s47, s65, -1
	s_add_i32 s48, 0, 0x10000
	s_cmp_eq_u32 s84, 28
	s_cselect_b32 s67, s17, s47
	s_cselect_b32 s66, s80, s46
	v_add_u32_e32 v140, s48, v142
	s_cselect_b32 s61, s13, s83
	s_cselect_b32 s60, s81, s82
	s_add_i32 s49, 0, 0x14000
	ds_read_b128 v[146:149], v140
	ds_read_b128 v[150:153], v140 offset:1024
	ds_read_b128 v[154:157], v140 offset:2048
	ds_read_b128 v[158:161], v140 offset:3072
	v_add_u32_e32 v140, s49, v142
	ds_read_b128 v[162:165], v140
	ds_read_b128 v[178:181], v140 offset:1024
	ds_read_b128 v[182:185], v140 offset:2048
	ds_read_b128 v[186:189], v140 offset:3072
	v_lshl_add_u64 v[140:141], s[64:65], 0, v[136:137]
	s_add_i32 m0, s23, 0xc000
	ds_read_b128 v[206:209], v144
	ds_read_b128 v[210:213], v144 offset:1024
	ds_read_b128 v[214:217], v144 offset:2048
	ds_read_b128 v[218:221], v144 offset:3072
	ds_read_b128 v[222:225], v144 offset:4096
	ds_read_b128 v[226:229], v144 offset:5120
	ds_read_b128 v[230:233], v144 offset:6144
	ds_read_b128 v[234:237], v144 offset:7168
	global_load_lds_dwordx4 v[140:141], off
	v_lshl_add_u64 v[140:141], s[64:65], 0, v[138:139]
	s_add_i32 m0, s23, 0xe000
	s_nop 0
	global_load_lds_dwordx4 v[140:141], off
	s_waitcnt vmcnt(8)
	s_waitcnt lgkmcnt(0)
	s_setprio 1
	s_waitcnt lgkmcnt(0)
	v_mfma_f32_16x16x32_bf16 v[126:129], v[146:149], v[206:209], v[126:129]
	v_mfma_f32_16x16x32_bf16 v[122:125], v[154:157], v[206:209], v[122:125]
	v_mfma_f32_16x16x32_bf16 v[110:113], v[146:149], v[214:217], v[110:113]
	v_mfma_f32_16x16x32_bf16 v[106:109], v[154:157], v[214:217], v[106:109]
	s_barrier
	v_mfma_f32_16x16x32_bf16 v[94:97], v[146:149], v[222:225], v[94:97]
	v_mfma_f32_16x16x32_bf16 v[90:93], v[154:157], v[222:225], v[90:93]
	v_mfma_f32_16x16x32_bf16 v[78:81], v[146:149], v[230:233], v[78:81]
	v_mfma_f32_16x16x32_bf16 v[74:77], v[154:157], v[230:233], v[74:77]
	v_mfma_f32_16x16x32_bf16 v[126:129], v[150:153], v[210:213], v[126:129]
	v_mfma_f32_16x16x32_bf16 v[122:125], v[158:161], v[210:213], v[122:125]
	v_mfma_f32_16x16x32_bf16 v[110:113], v[150:153], v[218:221], v[110:113]
	v_mfma_f32_16x16x32_bf16 v[106:109], v[158:161], v[218:221], v[106:109]
	v_mfma_f32_16x16x32_bf16 v[94:97], v[150:153], v[226:229], v[94:97]
	v_mfma_f32_16x16x32_bf16 v[90:93], v[158:161], v[226:229], v[90:93]
	v_mfma_f32_16x16x32_bf16 v[78:81], v[150:153], v[234:237], v[78:81]
	v_mfma_f32_16x16x32_bf16 v[74:77], v[158:161], v[234:237], v[74:77]
	s_setprio 0
	s_setprio 1
	v_mfma_f32_16x16x32_bf16 v[118:121], v[162:165], v[206:209], v[118:121]
	v_mfma_f32_16x16x32_bf16 v[114:117], v[182:185], v[206:209], v[114:117]
	v_mfma_f32_16x16x32_bf16 v[102:105], v[162:165], v[214:217], v[102:105]
	v_mfma_f32_16x16x32_bf16 v[98:101], v[182:185], v[214:217], v[98:101]
	v_mfma_f32_16x16x32_bf16 v[86:89], v[162:165], v[222:225], v[86:89]
	v_mfma_f32_16x16x32_bf16 v[82:85], v[182:185], v[222:225], v[82:85]
	v_mfma_f32_16x16x32_bf16 v[70:73], v[162:165], v[230:233], v[70:73]
	v_mfma_f32_16x16x32_bf16 v[66:69], v[182:185], v[230:233], v[66:69]
	v_mfma_f32_16x16x32_bf16 v[118:121], v[178:181], v[210:213], v[118:121]
	v_mfma_f32_16x16x32_bf16 v[114:117], v[186:189], v[210:213], v[114:117]
	v_mfma_f32_16x16x32_bf16 v[102:105], v[178:181], v[218:221], v[102:105]
	v_mfma_f32_16x16x32_bf16 v[98:101], v[186:189], v[218:221], v[98:101]
	v_mfma_f32_16x16x32_bf16 v[86:89], v[178:181], v[226:229], v[86:89]
	v_mfma_f32_16x16x32_bf16 v[82:85], v[186:189], v[226:229], v[82:85]
	v_mfma_f32_16x16x32_bf16 v[70:73], v[178:181], v[234:237], v[70:73]
	v_mfma_f32_16x16x32_bf16 v[66:69], v[186:189], v[234:237], v[66:69]
	s_setprio 0
	s_barrier
	s_add_i32 s46, s48, s72
	v_lshl_add_u64 v[140:141], s[60:61], 0, v[166:167]
	s_mov_b32 m0, s46
	ds_read_b128 v[206:209], v144 offset:16384
	ds_read_b128 v[210:213], v144 offset:17408
	ds_read_b128 v[214:217], v144 offset:18432
	ds_read_b128 v[218:221], v144 offset:19456
	ds_read_b128 v[222:225], v144 offset:20480
	ds_read_b128 v[226:229], v144 offset:21504
	ds_read_b128 v[230:233], v144 offset:22528
	ds_read_b128 v[234:237], v144 offset:23552
	global_load_lds_dwordx4 v[140:141], off
	s_add_i32 m0, s46, 0x2000
	s_add_u32 s46, s60, 0x80000
	v_lshl_add_u64 v[242:243], s[60:61], 0, v[134:135]
	s_addc_u32 s47, s61, 0
	s_add_i32 s48, s49, s72
	global_load_lds_dwordx4 v[242:243], off
	v_lshl_add_u64 v[244:245], s[46:47], 0, v[166:167]
	s_mov_b32 m0, s48
	v_lshl_add_u64 v[246:247], s[66:67], 0, v[132:133]
	global_load_lds_dwordx4 v[244:245], off
	v_lshl_add_u64 v[244:245], s[46:47], 0, v[134:135]
	s_add_i32 m0, s48, 0x2000
	s_nop 0
	global_load_lds_dwordx4 v[244:245], off
	v_lshl_add_u64 v[244:245], s[66:67], 0, v[130:131]
	s_mov_b32 m0, s23
	s_nop 0
	global_load_lds_dwordx4 v[244:245], off
	s_mov_b32 m0, s73
	s_nop 0
	global_load_lds_dwordx4 v[246:247], off
	s_waitcnt vmcnt(8)
	s_waitcnt lgkmcnt(0)
	s_setprio 1
	s_waitcnt lgkmcnt(0)
	v_mfma_f32_16x16x32_bf16 v[62:65], v[146:149], v[206:209], v[62:65]
	v_mfma_f32_16x16x32_bf16 v[58:61], v[154:157], v[206:209], v[58:61]
	v_mfma_f32_16x16x32_bf16 v[46:49], v[146:149], v[214:217], v[46:49]
	v_mfma_f32_16x16x32_bf16 v[42:45], v[154:157], v[214:217], v[42:45]
	s_barrier
	v_mfma_f32_16x16x32_bf16 v[30:33], v[146:149], v[222:225], v[30:33]
	v_mfma_f32_16x16x32_bf16 v[26:29], v[154:157], v[222:225], v[26:29]
	v_mfma_f32_16x16x32_bf16 v[14:17], v[146:149], v[230:233], v[14:17]
	v_mfma_f32_16x16x32_bf16 v[10:13], v[154:157], v[230:233], v[10:13]
	v_mfma_f32_16x16x32_bf16 v[62:65], v[150:153], v[210:213], v[62:65]
	v_mfma_f32_16x16x32_bf16 v[58:61], v[158:161], v[210:213], v[58:61]
	v_mfma_f32_16x16x32_bf16 v[46:49], v[150:153], v[218:221], v[46:49]
	v_mfma_f32_16x16x32_bf16 v[42:45], v[158:161], v[218:221], v[42:45]
	v_mfma_f32_16x16x32_bf16 v[30:33], v[150:153], v[226:229], v[30:33]
	v_mfma_f32_16x16x32_bf16 v[26:29], v[158:161], v[226:229], v[26:29]
	v_mfma_f32_16x16x32_bf16 v[14:17], v[150:153], v[234:237], v[14:17]
	v_mfma_f32_16x16x32_bf16 v[10:13], v[158:161], v[234:237], v[10:13]
	s_setprio 0
	s_setprio 1
	v_mfma_f32_16x16x32_bf16 v[54:57], v[162:165], v[206:209], v[54:57]
	v_mfma_f32_16x16x32_bf16 v[50:53], v[182:185], v[206:209], v[50:53]
	v_mfma_f32_16x16x32_bf16 v[38:41], v[162:165], v[214:217], v[38:41]
	v_mfma_f32_16x16x32_bf16 v[34:37], v[182:185], v[214:217], v[34:37]
	v_mfma_f32_16x16x32_bf16 v[22:25], v[162:165], v[222:225], v[22:25]
	v_mfma_f32_16x16x32_bf16 v[18:21], v[182:185], v[222:225], v[18:21]
	v_mfma_f32_16x16x32_bf16 v[6:9], v[162:165], v[230:233], v[6:9]
	v_mfma_f32_16x16x32_bf16 v[2:5], v[182:185], v[230:233], v[2:5]
	v_mfma_f32_16x16x32_bf16 v[54:57], v[178:181], v[210:213], v[54:57]
	v_mfma_f32_16x16x32_bf16 v[50:53], v[186:189], v[210:213], v[50:53]
	v_mfma_f32_16x16x32_bf16 v[38:41], v[178:181], v[218:221], v[38:41]
	v_mfma_f32_16x16x32_bf16 v[34:37], v[186:189], v[218:221], v[34:37]
	v_mfma_f32_16x16x32_bf16 v[22:25], v[178:181], v[226:229], v[22:25]
	v_mfma_f32_16x16x32_bf16 v[18:21], v[186:189], v[226:229], v[18:21]
	v_mfma_f32_16x16x32_bf16 v[6:9], v[178:181], v[234:237], v[6:9]
	v_mfma_f32_16x16x32_bf16 v[2:5], v[186:189], v[234:237], v[2:5]
	s_setprio 0
	s_barrier
	s_add_i32 s48, 0, 0x18000
	v_add_u32_e32 v145, s48, v142
	s_add_i32 s49, 0, 0x1c000
	ds_read_b128 v[146:149], v145
	ds_read_b128 v[150:153], v145 offset:1024
	ds_read_b128 v[154:157], v145 offset:2048
	ds_read_b128 v[158:161], v145 offset:3072
	v_add_u32_e32 v145, s49, v142
	ds_read_b128 v[162:165], v145
	ds_read_b128 v[178:181], v145 offset:1024
	ds_read_b128 v[182:185], v145 offset:2048
	ds_read_b128 v[186:189], v145 offset:3072
	s_add_u32 s46, s66, 0x80000
	s_addc_u32 s47, s67, 0
	s_mov_b32 m0, s74
	v_lshl_add_u64 v[248:249], s[46:47], 0, v[130:131]
	ds_read_b128 v[206:209], v144 offset:32768
	ds_read_b128 v[210:213], v144 offset:33792
	ds_read_b128 v[214:217], v144 offset:34816
	ds_read_b128 v[218:221], v144 offset:35840
	ds_read_b128 v[222:225], v144 offset:36864
	ds_read_b128 v[226:229], v144 offset:37888
	ds_read_b128 v[230:233], v144 offset:38912
	ds_read_b128 v[234:237], v144 offset:39936
	global_load_lds_dwordx4 v[248:249], off
	v_lshl_add_u64 v[248:249], s[46:47], 0, v[132:133]
	s_mov_b32 m0, s75
	s_nop 0
	global_load_lds_dwordx4 v[248:249], off
	s_waitcnt vmcnt(8)
	s_waitcnt lgkmcnt(0)
	s_setprio 1
	s_waitcnt lgkmcnt(0)
	v_mfma_f32_16x16x32_bf16 v[126:129], v[146:149], v[206:209], v[126:129]
	v_mfma_f32_16x16x32_bf16 v[122:125], v[154:157], v[206:209], v[122:125]
	v_mfma_f32_16x16x32_bf16 v[110:113], v[146:149], v[214:217], v[110:113]
	v_mfma_f32_16x16x32_bf16 v[106:109], v[154:157], v[214:217], v[106:109]
	s_barrier
	v_mfma_f32_16x16x32_bf16 v[94:97], v[146:149], v[222:225], v[94:97]
	v_mfma_f32_16x16x32_bf16 v[90:93], v[154:157], v[222:225], v[90:93]
	v_mfma_f32_16x16x32_bf16 v[78:81], v[146:149], v[230:233], v[78:81]
	v_mfma_f32_16x16x32_bf16 v[74:77], v[154:157], v[230:233], v[74:77]
	v_mfma_f32_16x16x32_bf16 v[126:129], v[150:153], v[210:213], v[126:129]
	v_mfma_f32_16x16x32_bf16 v[122:125], v[158:161], v[210:213], v[122:125]
	v_mfma_f32_16x16x32_bf16 v[110:113], v[150:153], v[218:221], v[110:113]
	v_mfma_f32_16x16x32_bf16 v[106:109], v[158:161], v[218:221], v[106:109]
	v_mfma_f32_16x16x32_bf16 v[94:97], v[150:153], v[226:229], v[94:97]
	v_mfma_f32_16x16x32_bf16 v[90:93], v[158:161], v[226:229], v[90:93]
	v_mfma_f32_16x16x32_bf16 v[78:81], v[150:153], v[234:237], v[78:81]
	v_mfma_f32_16x16x32_bf16 v[74:77], v[158:161], v[234:237], v[74:77]
	s_setprio 0
	s_setprio 1
	v_mfma_f32_16x16x32_bf16 v[118:121], v[162:165], v[206:209], v[118:121]
	v_mfma_f32_16x16x32_bf16 v[114:117], v[182:185], v[206:209], v[114:117]
	v_mfma_f32_16x16x32_bf16 v[102:105], v[162:165], v[214:217], v[102:105]
	v_mfma_f32_16x16x32_bf16 v[98:101], v[182:185], v[214:217], v[98:101]
	v_mfma_f32_16x16x32_bf16 v[86:89], v[162:165], v[222:225], v[86:89]
	v_mfma_f32_16x16x32_bf16 v[82:85], v[182:185], v[222:225], v[82:85]
	v_mfma_f32_16x16x32_bf16 v[70:73], v[162:165], v[230:233], v[70:73]
	v_mfma_f32_16x16x32_bf16 v[66:69], v[182:185], v[230:233], v[66:69]
	v_mfma_f32_16x16x32_bf16 v[118:121], v[178:181], v[210:213], v[118:121]
	v_mfma_f32_16x16x32_bf16 v[114:117], v[186:189], v[210:213], v[114:117]
	v_mfma_f32_16x16x32_bf16 v[102:105], v[178:181], v[218:221], v[102:105]
	v_mfma_f32_16x16x32_bf16 v[98:101], v[186:189], v[218:221], v[98:101]
	v_mfma_f32_16x16x32_bf16 v[86:89], v[178:181], v[226:229], v[86:89]
	v_mfma_f32_16x16x32_bf16 v[82:85], v[186:189], v[226:229], v[82:85]
	v_mfma_f32_16x16x32_bf16 v[70:73], v[178:181], v[234:237], v[70:73]
	v_mfma_f32_16x16x32_bf16 v[66:69], v[186:189], v[234:237], v[66:69]
	s_setprio 0
	s_barrier
	s_add_i32 s46, s48, s72
	v_lshl_add_u64 v[140:141], v[140:141], 0, s[42:43]
	s_mov_b32 m0, s46
	ds_read_b128 v[206:209], v144 offset:49152
	ds_read_b128 v[210:213], v144 offset:50176
	ds_read_b128 v[214:217], v144 offset:51200
	ds_read_b128 v[218:221], v144 offset:52224
	ds_read_b128 v[222:225], v144 offset:53248
	ds_read_b128 v[226:229], v144 offset:54272
	ds_read_b128 v[230:233], v144 offset:55296
	ds_read_b128 v[234:237], v144 offset:56320
	global_load_lds_dwordx4 v[140:141], off
	s_add_i32 m0, s46, 0x2000
	s_add_u32 s46, s60, 0x80080
	v_lshl_add_u64 v[140:141], v[242:243], 0, s[42:43]
	s_addc_u32 s47, s61, 0
	s_add_i32 s48, s49, s72
	global_load_lds_dwordx4 v[140:141], off
	v_lshl_add_u64 v[140:141], s[46:47], 0, v[166:167]
	s_mov_b32 m0, s48
	s_nop 0
	global_load_lds_dwordx4 v[140:141], off
	v_lshl_add_u64 v[140:141], s[46:47], 0, v[134:135]
	s_add_i32 m0, s48, 0x2000
	s_nop 0
	global_load_lds_dwordx4 v[140:141], off
	v_lshl_add_u64 v[140:141], v[244:245], 0, s[42:43]
	s_mov_b32 m0, s76
	s_nop 0
	global_load_lds_dwordx4 v[140:141], off
	v_lshl_add_u64 v[140:141], v[246:247], 0, s[42:43]
	s_mov_b32 m0, s77
	s_nop 0
	global_load_lds_dwordx4 v[140:141], off
	s_waitcnt vmcnt(8)
	s_waitcnt lgkmcnt(0)
	s_setprio 1
	s_waitcnt lgkmcnt(0)
	v_mfma_f32_16x16x32_bf16 v[62:65], v[146:149], v[206:209], v[62:65]
	v_mfma_f32_16x16x32_bf16 v[58:61], v[154:157], v[206:209], v[58:61]
	v_mfma_f32_16x16x32_bf16 v[46:49], v[146:149], v[214:217], v[46:49]
	v_mfma_f32_16x16x32_bf16 v[42:45], v[154:157], v[214:217], v[42:45]
	s_barrier
	v_mfma_f32_16x16x32_bf16 v[30:33], v[146:149], v[222:225], v[30:33]
	v_mfma_f32_16x16x32_bf16 v[26:29], v[154:157], v[222:225], v[26:29]
	v_mfma_f32_16x16x32_bf16 v[14:17], v[146:149], v[230:233], v[14:17]
	v_mfma_f32_16x16x32_bf16 v[10:13], v[154:157], v[230:233], v[10:13]
	v_mfma_f32_16x16x32_bf16 v[62:65], v[150:153], v[210:213], v[62:65]
	v_mfma_f32_16x16x32_bf16 v[58:61], v[158:161], v[210:213], v[58:61]
	v_mfma_f32_16x16x32_bf16 v[46:49], v[150:153], v[218:221], v[46:49]
	v_mfma_f32_16x16x32_bf16 v[42:45], v[158:161], v[218:221], v[42:45]
	v_mfma_f32_16x16x32_bf16 v[30:33], v[150:153], v[226:229], v[30:33]
	v_mfma_f32_16x16x32_bf16 v[26:29], v[158:161], v[226:229], v[26:29]
	v_mfma_f32_16x16x32_bf16 v[14:17], v[150:153], v[234:237], v[14:17]
	v_mfma_f32_16x16x32_bf16 v[10:13], v[158:161], v[234:237], v[10:13]
	s_setprio 0
	s_setprio 1
	v_mfma_f32_16x16x32_bf16 v[54:57], v[162:165], v[206:209], v[54:57]
	v_mfma_f32_16x16x32_bf16 v[50:53], v[182:185], v[206:209], v[50:53]
	v_mfma_f32_16x16x32_bf16 v[38:41], v[162:165], v[214:217], v[38:41]
	v_mfma_f32_16x16x32_bf16 v[34:37], v[182:185], v[214:217], v[34:37]
	v_mfma_f32_16x16x32_bf16 v[22:25], v[162:165], v[222:225], v[22:25]
	v_mfma_f32_16x16x32_bf16 v[18:21], v[182:185], v[222:225], v[18:21]
	v_mfma_f32_16x16x32_bf16 v[6:9], v[162:165], v[230:233], v[6:9]
	v_mfma_f32_16x16x32_bf16 v[2:5], v[182:185], v[230:233], v[2:5]
	v_mfma_f32_16x16x32_bf16 v[54:57], v[178:181], v[210:213], v[54:57]
	v_mfma_f32_16x16x32_bf16 v[50:53], v[186:189], v[210:213], v[50:53]
	v_mfma_f32_16x16x32_bf16 v[38:41], v[178:181], v[218:221], v[38:41]
	v_mfma_f32_16x16x32_bf16 v[34:37], v[186:189], v[218:221], v[34:37]
	v_mfma_f32_16x16x32_bf16 v[22:25], v[178:181], v[226:229], v[22:25]
	v_mfma_f32_16x16x32_bf16 v[18:21], v[186:189], v[226:229], v[18:21]
	v_mfma_f32_16x16x32_bf16 v[6:9], v[178:181], v[234:237], v[6:9]
	v_mfma_f32_16x16x32_bf16 v[2:5], v[186:189], v[234:237], v[2:5]
	s_setprio 0
	s_barrier
	s_add_i32 s84, s84, 2
	s_add_u32 s64, s64, 0x100
	s_addc_u32 s65, s65, 0
	s_add_u32 s82, s82, 0x100
	s_addc_u32 s83, s83, 0
	s_cmp_gt_u32 s84, 29
	s_cbranch_scc0 .LBB0_1035
	s_and_b64 vcc, exec, s[10:11]
	s_cbranch_vccz .LBB0_1038
	s_barrier

.LBB0_1112:
	s_add_u32 s46, s64, 0xffe00080
	s_addc_u32 s47, s65, -1
	s_add_i32 s48, 0, 0x10000
	s_cmpk_eq_i32 s84, 0x7c
	s_cselect_b32 s67, s19, s47
	s_cselect_b32 s66, s80, s46
	s_cselect_b32 s61, s17, s83
	s_cselect_b32 s60, s81, s82
	s_add_i32 s49, 0, 0x14000
	v_add_u32_e32 v142, s48, v182
	v_add_u32_e32 v164, s49, v182
	ds_read_b128 v[130:133], v142
	ds_read_b128 v[134:137], v142 offset:1024
	ds_read_b128 v[138:141], v142 offset:2048
	ds_read_b128 v[142:145], v142 offset:3072
	ds_read_b128 v[146:149], v164
	ds_read_b128 v[160:163], v164 offset:1024
	ds_read_b128 v[178:181], v164 offset:2048
	ds_read_b128 v[186:189], v164 offset:3072
	v_lshl_add_u64 v[164:165], s[64:65], 0, v[156:157]
	s_add_i32 m0, s63, 0xc000
	ds_read_b128 v[206:209], v184
	ds_read_b128 v[210:213], v184 offset:1024
	ds_read_b128 v[214:217], v184 offset:2048
	ds_read_b128 v[218:221], v184 offset:3072
	ds_read_b128 v[222:225], v184 offset:4096
	ds_read_b128 v[226:229], v184 offset:5120
	ds_read_b128 v[230:233], v184 offset:6144
	ds_read_b128 v[234:237], v184 offset:7168
	global_load_lds_dwordx4 v[164:165], off
	v_lshl_add_u64 v[164:165], s[64:65], 0, v[158:159]
	s_add_i32 m0, s63, 0xe000
	s_nop 0
	global_load_lds_dwordx4 v[164:165], off
	s_waitcnt vmcnt(8)
	s_waitcnt lgkmcnt(0)
	s_setprio 1
	s_waitcnt lgkmcnt(0)
	v_mfma_f32_16x16x32_bf16 v[126:129], v[130:133], v[206:209], v[126:129]
	v_mfma_f32_16x16x32_bf16 v[122:125], v[138:141], v[206:209], v[122:125]
	v_mfma_f32_16x16x32_bf16 v[118:121], v[130:133], v[214:217], v[118:121]
	v_mfma_f32_16x16x32_bf16 v[114:117], v[138:141], v[214:217], v[114:117]
	s_barrier
	v_mfma_f32_16x16x32_bf16 v[94:97], v[130:133], v[222:225], v[94:97]
	v_mfma_f32_16x16x32_bf16 v[90:93], v[138:141], v[222:225], v[90:93]
	v_mfma_f32_16x16x32_bf16 v[82:85], v[130:133], v[230:233], v[82:85]
	v_mfma_f32_16x16x32_bf16 v[74:77], v[138:141], v[230:233], v[74:77]
	v_mfma_f32_16x16x32_bf16 v[126:129], v[134:137], v[210:213], v[126:129]
	v_mfma_f32_16x16x32_bf16 v[122:125], v[142:145], v[210:213], v[122:125]
	v_mfma_f32_16x16x32_bf16 v[118:121], v[134:137], v[218:221], v[118:121]
	v_mfma_f32_16x16x32_bf16 v[114:117], v[142:145], v[218:221], v[114:117]
	v_mfma_f32_16x16x32_bf16 v[94:97], v[134:137], v[226:229], v[94:97]
	v_mfma_f32_16x16x32_bf16 v[90:93], v[142:145], v[226:229], v[90:93]
	v_mfma_f32_16x16x32_bf16 v[82:85], v[134:137], v[234:237], v[82:85]
	v_mfma_f32_16x16x32_bf16 v[74:77], v[142:145], v[234:237], v[74:77]
	s_setprio 0
	s_setprio 1
	v_mfma_f32_16x16x32_bf16 v[110:113], v[146:149], v[206:209], v[110:113]
	v_mfma_f32_16x16x32_bf16 v[106:109], v[178:181], v[206:209], v[106:109]
	v_mfma_f32_16x16x32_bf16 v[102:105], v[146:149], v[214:217], v[102:105]
	v_mfma_f32_16x16x32_bf16 v[98:101], v[178:181], v[214:217], v[98:101]
	v_mfma_f32_16x16x32_bf16 v[86:89], v[146:149], v[222:225], v[86:89]
	v_mfma_f32_16x16x32_bf16 v[78:81], v[178:181], v[222:225], v[78:81]
	v_mfma_f32_16x16x32_bf16 v[70:73], v[146:149], v[230:233], v[70:73]
	v_mfma_f32_16x16x32_bf16 v[66:69], v[178:181], v[230:233], v[66:69]
	v_mfma_f32_16x16x32_bf16 v[110:113], v[160:163], v[210:213], v[110:113]
	v_mfma_f32_16x16x32_bf16 v[106:109], v[186:189], v[210:213], v[106:109]
	v_mfma_f32_16x16x32_bf16 v[102:105], v[160:163], v[218:221], v[102:105]
	v_mfma_f32_16x16x32_bf16 v[98:101], v[186:189], v[218:221], v[98:101]
	v_mfma_f32_16x16x32_bf16 v[86:89], v[160:163], v[226:229], v[86:89]
	v_mfma_f32_16x16x32_bf16 v[78:81], v[186:189], v[226:229], v[78:81]
	v_mfma_f32_16x16x32_bf16 v[70:73], v[160:163], v[234:237], v[70:73]
	v_mfma_f32_16x16x32_bf16 v[66:69], v[186:189], v[234:237], v[66:69]
	s_setprio 0
	s_barrier
	s_add_i32 s46, s48, s72
	v_lshl_add_u64 v[164:165], s[60:61], 0, v[166:167]
	s_mov_b32 m0, s46
	ds_read_b128 v[206:209], v184 offset:16384
	ds_read_b128 v[210:213], v184 offset:17408
	ds_read_b128 v[214:217], v184 offset:18432
	ds_read_b128 v[218:221], v184 offset:19456
	ds_read_b128 v[222:225], v184 offset:20480
	ds_read_b128 v[226:229], v184 offset:21504
	ds_read_b128 v[230:233], v184 offset:22528
	ds_read_b128 v[234:237], v184 offset:23552
	global_load_lds_dwordx4 v[164:165], off
	s_add_i32 m0, s46, 0x2000
	s_add_u32 s46, s60, 0x200000
	v_lshl_add_u64 v[242:243], s[60:61], 0, v[154:155]
	s_addc_u32 s47, s61, 0
	s_add_i32 s48, s49, s72
	global_load_lds_dwordx4 v[242:243], off
	v_lshl_add_u64 v[244:245], s[46:47], 0, v[166:167]
	s_mov_b32 m0, s48
	v_lshl_add_u64 v[246:247], s[66:67], 0, v[152:153]
	global_load_lds_dwordx4 v[244:245], off
	v_lshl_add_u64 v[244:245], s[46:47], 0, v[154:155]
	s_add_i32 m0, s48, 0x2000
	s_nop 0
	global_load_lds_dwordx4 v[244:245], off
	v_lshl_add_u64 v[244:245], s[66:67], 0, v[150:151]
	s_mov_b32 m0, s63
	s_nop 0
	global_load_lds_dwordx4 v[244:245], off
	s_mov_b32 m0, s73
	s_nop 0
	global_load_lds_dwordx4 v[246:247], off
	s_waitcnt vmcnt(8)
	s_waitcnt lgkmcnt(0)
	s_setprio 1
	s_waitcnt lgkmcnt(0)
	v_mfma_f32_16x16x32_bf16 v[62:65], v[130:133], v[206:209], v[62:65]
	v_mfma_f32_16x16x32_bf16 v[58:61], v[138:141], v[206:209], v[58:61]
	v_mfma_f32_16x16x32_bf16 v[50:53], v[130:133], v[214:217], v[50:53]
	v_mfma_f32_16x16x32_bf16 v[42:45], v[138:141], v[214:217], v[42:45]
	s_barrier
	v_mfma_f32_16x16x32_bf16 v[34:37], v[130:133], v[222:225], v[34:37]
	v_mfma_f32_16x16x32_bf16 v[26:29], v[138:141], v[222:225], v[26:29]
	v_mfma_f32_16x16x32_bf16 v[18:21], v[130:133], v[230:233], v[18:21]
	v_mfma_f32_16x16x32_bf16 v[10:13], v[138:141], v[230:233], v[10:13]
	v_mfma_f32_16x16x32_bf16 v[62:65], v[134:137], v[210:213], v[62:65]
	v_mfma_f32_16x16x32_bf16 v[58:61], v[142:145], v[210:213], v[58:61]
	v_mfma_f32_16x16x32_bf16 v[50:53], v[134:137], v[218:221], v[50:53]
	v_mfma_f32_16x16x32_bf16 v[42:45], v[142:145], v[218:221], v[42:45]
	v_mfma_f32_16x16x32_bf16 v[34:37], v[134:137], v[226:229], v[34:37]
	v_mfma_f32_16x16x32_bf16 v[26:29], v[142:145], v[226:229], v[26:29]
	v_mfma_f32_16x16x32_bf16 v[18:21], v[134:137], v[234:237], v[18:21]
	v_mfma_f32_16x16x32_bf16 v[10:13], v[142:145], v[234:237], v[10:13]
	s_setprio 0
	s_setprio 1
	v_mfma_f32_16x16x32_bf16 v[54:57], v[146:149], v[206:209], v[54:57]
	v_mfma_f32_16x16x32_bf16 v[46:49], v[178:181], v[206:209], v[46:49]
	v_mfma_f32_16x16x32_bf16 v[38:41], v[146:149], v[214:217], v[38:41]
	v_mfma_f32_16x16x32_bf16 v[30:33], v[178:181], v[214:217], v[30:33]
	v_mfma_f32_16x16x32_bf16 v[22:25], v[146:149], v[222:225], v[22:25]
	v_mfma_f32_16x16x32_bf16 v[14:17], v[178:181], v[222:225], v[14:17]
	v_mfma_f32_16x16x32_bf16 v[6:9], v[146:149], v[230:233], v[6:9]
	v_mfma_f32_16x16x32_bf16 v[2:5], v[178:181], v[230:233], v[2:5]
	v_mfma_f32_16x16x32_bf16 v[54:57], v[160:163], v[210:213], v[54:57]
	v_mfma_f32_16x16x32_bf16 v[46:49], v[186:189], v[210:213], v[46:49]
	v_mfma_f32_16x16x32_bf16 v[38:41], v[160:163], v[218:221], v[38:41]
	v_mfma_f32_16x16x32_bf16 v[30:33], v[186:189], v[218:221], v[30:33]
	v_mfma_f32_16x16x32_bf16 v[22:25], v[160:163], v[226:229], v[22:25]
	v_mfma_f32_16x16x32_bf16 v[14:17], v[186:189], v[226:229], v[14:17]
	v_mfma_f32_16x16x32_bf16 v[6:9], v[160:163], v[234:237], v[6:9]
	v_mfma_f32_16x16x32_bf16 v[2:5], v[186:189], v[234:237], v[2:5]
	s_setprio 0
	s_barrier
	s_add_i32 s48, 0, 0x18000
	s_add_i32 s49, 0, 0x1c000
	v_add_u32_e32 v142, s48, v182
	v_add_u32_e32 v185, s49, v182
	ds_read_b128 v[130:133], v142
	ds_read_b128 v[134:137], v142 offset:1024
	ds_read_b128 v[138:141], v142 offset:2048
	ds_read_b128 v[142:145], v142 offset:3072
	ds_read_b128 v[146:149], v185
	ds_read_b128 v[160:163], v185 offset:1024
	ds_read_b128 v[178:181], v185 offset:2048
	ds_read_b128 v[186:189], v185 offset:3072
	s_add_u32 s46, s66, 0x200000
	s_addc_u32 s47, s67, 0
	s_mov_b32 m0, s74
	v_lshl_add_u64 v[248:249], s[46:47], 0, v[150:151]
	ds_read_b128 v[206:209], v184 offset:32768
	ds_read_b128 v[210:213], v184 offset:33792
	ds_read_b128 v[214:217], v184 offset:34816
	ds_read_b128 v[218:221], v184 offset:35840
	ds_read_b128 v[222:225], v184 offset:36864
	ds_read_b128 v[226:229], v184 offset:37888
	ds_read_b128 v[230:233], v184 offset:38912
	ds_read_b128 v[234:237], v184 offset:39936
	global_load_lds_dwordx4 v[248:249], off
	v_lshl_add_u64 v[248:249], s[46:47], 0, v[152:153]
	s_mov_b32 m0, s75
	s_nop 0
	global_load_lds_dwordx4 v[248:249], off
	s_waitcnt vmcnt(8)
	s_waitcnt lgkmcnt(0)
	s_setprio 1
	s_waitcnt lgkmcnt(0)
	v_mfma_f32_16x16x32_bf16 v[126:129], v[130:133], v[206:209], v[126:129]
	v_mfma_f32_16x16x32_bf16 v[122:125], v[138:141], v[206:209], v[122:125]
	v_mfma_f32_16x16x32_bf16 v[118:121], v[130:133], v[214:217], v[118:121]
	v_mfma_f32_16x16x32_bf16 v[114:117], v[138:141], v[214:217], v[114:117]
	s_barrier
	v_mfma_f32_16x16x32_bf16 v[94:97], v[130:133], v[222:225], v[94:97]
	v_mfma_f32_16x16x32_bf16 v[90:93], v[138:141], v[222:225], v[90:93]
	v_mfma_f32_16x16x32_bf16 v[82:85], v[130:133], v[230:233], v[82:85]
	v_mfma_f32_16x16x32_bf16 v[74:77], v[138:141], v[230:233], v[74:77]
	v_mfma_f32_16x16x32_bf16 v[126:129], v[134:137], v[210:213], v[126:129]
	v_mfma_f32_16x16x32_bf16 v[122:125], v[142:145], v[210:213], v[122:125]
	v_mfma_f32_16x16x32_bf16 v[118:121], v[134:137], v[218:221], v[118:121]
	v_mfma_f32_16x16x32_bf16 v[114:117], v[142:145], v[218:221], v[114:117]
	v_mfma_f32_16x16x32_bf16 v[94:97], v[134:137], v[226:229], v[94:97]
	v_mfma_f32_16x16x32_bf16 v[90:93], v[142:145], v[226:229], v[90:93]
	v_mfma_f32_16x16x32_bf16 v[82:85], v[134:137], v[234:237], v[82:85]
	v_mfma_f32_16x16x32_bf16 v[74:77], v[142:145], v[234:237], v[74:77]
	s_setprio 0
	s_setprio 1
	v_mfma_f32_16x16x32_bf16 v[110:113], v[146:149], v[206:209], v[110:113]
	v_mfma_f32_16x16x32_bf16 v[106:109], v[178:181], v[206:209], v[106:109]
	v_mfma_f32_16x16x32_bf16 v[102:105], v[146:149], v[214:217], v[102:105]
	v_mfma_f32_16x16x32_bf16 v[98:101], v[178:181], v[214:217], v[98:101]
	v_mfma_f32_16x16x32_bf16 v[86:89], v[146:149], v[222:225], v[86:89]
	v_mfma_f32_16x16x32_bf16 v[78:81], v[178:181], v[222:225], v[78:81]
	v_mfma_f32_16x16x32_bf16 v[70:73], v[146:149], v[230:233], v[70:73]
	v_mfma_f32_16x16x32_bf16 v[66:69], v[178:181], v[230:233], v[66:69]
	v_mfma_f32_16x16x32_bf16 v[110:113], v[160:163], v[210:213], v[110:113]
	v_mfma_f32_16x16x32_bf16 v[106:109], v[186:189], v[210:213], v[106:109]
	v_mfma_f32_16x16x32_bf16 v[102:105], v[160:163], v[218:221], v[102:105]
	v_mfma_f32_16x16x32_bf16 v[98:101], v[186:189], v[218:221], v[98:101]
	v_mfma_f32_16x16x32_bf16 v[86:89], v[160:163], v[226:229], v[86:89]
	v_mfma_f32_16x16x32_bf16 v[78:81], v[186:189], v[226:229], v[78:81]
	v_mfma_f32_16x16x32_bf16 v[70:73], v[160:163], v[234:237], v[70:73]
	v_mfma_f32_16x16x32_bf16 v[66:69], v[186:189], v[234:237], v[66:69]
	s_setprio 0
	s_barrier
	s_add_i32 s46, s48, s72
	v_lshl_add_u64 v[164:165], v[164:165], 0, s[42:43]
	s_mov_b32 m0, s46
	ds_read_b128 v[206:209], v184 offset:49152
	ds_read_b128 v[210:213], v184 offset:50176
	ds_read_b128 v[214:217], v184 offset:51200
	ds_read_b128 v[218:221], v184 offset:52224
	ds_read_b128 v[222:225], v184 offset:53248
	ds_read_b128 v[226:229], v184 offset:54272
	ds_read_b128 v[230:233], v184 offset:55296
	ds_read_b128 v[234:237], v184 offset:56320
	global_load_lds_dwordx4 v[164:165], off
	s_add_i32 m0, s46, 0x2000
	s_add_u32 s46, s60, 0x200080
	v_lshl_add_u64 v[164:165], v[242:243], 0, s[42:43]
	s_addc_u32 s47, s61, 0
	s_add_i32 s48, s49, s72
	global_load_lds_dwordx4 v[164:165], off
	v_lshl_add_u64 v[164:165], s[46:47], 0, v[166:167]
	s_mov_b32 m0, s48
	s_nop 0
	global_load_lds_dwordx4 v[164:165], off
	v_lshl_add_u64 v[164:165], s[46:47], 0, v[154:155]
	s_add_i32 m0, s48, 0x2000
	s_nop 0
	global_load_lds_dwordx4 v[164:165], off
	v_lshl_add_u64 v[164:165], v[244:245], 0, s[42:43]
	s_mov_b32 m0, s76
	s_nop 0
	global_load_lds_dwordx4 v[164:165], off
	v_lshl_add_u64 v[164:165], v[246:247], 0, s[42:43]
	s_mov_b32 m0, s77
	s_nop 0
	global_load_lds_dwordx4 v[164:165], off
	s_waitcnt vmcnt(8)
	s_waitcnt lgkmcnt(0)
	s_setprio 1
	s_waitcnt lgkmcnt(0)
	v_mfma_f32_16x16x32_bf16 v[62:65], v[130:133], v[206:209], v[62:65]
	v_mfma_f32_16x16x32_bf16 v[58:61], v[138:141], v[206:209], v[58:61]
	v_mfma_f32_16x16x32_bf16 v[50:53], v[130:133], v[214:217], v[50:53]
	v_mfma_f32_16x16x32_bf16 v[42:45], v[138:141], v[214:217], v[42:45]
	s_barrier
	v_mfma_f32_16x16x32_bf16 v[34:37], v[130:133], v[222:225], v[34:37]
	v_mfma_f32_16x16x32_bf16 v[26:29], v[138:141], v[222:225], v[26:29]
	v_mfma_f32_16x16x32_bf16 v[18:21], v[130:133], v[230:233], v[18:21]
	v_mfma_f32_16x16x32_bf16 v[10:13], v[138:141], v[230:233], v[10:13]
	v_mfma_f32_16x16x32_bf16 v[62:65], v[134:137], v[210:213], v[62:65]
	v_mfma_f32_16x16x32_bf16 v[58:61], v[142:145], v[210:213], v[58:61]
	v_mfma_f32_16x16x32_bf16 v[50:53], v[134:137], v[218:221], v[50:53]
	v_mfma_f32_16x16x32_bf16 v[42:45], v[142:145], v[218:221], v[42:45]
	v_mfma_f32_16x16x32_bf16 v[34:37], v[134:137], v[226:229], v[34:37]
	v_mfma_f32_16x16x32_bf16 v[26:29], v[142:145], v[226:229], v[26:29]
	v_mfma_f32_16x16x32_bf16 v[18:21], v[134:137], v[234:237], v[18:21]
	v_mfma_f32_16x16x32_bf16 v[10:13], v[142:145], v[234:237], v[10:13]
	s_setprio 0
	s_setprio 1
	v_mfma_f32_16x16x32_bf16 v[54:57], v[146:149], v[206:209], v[54:57]
	v_mfma_f32_16x16x32_bf16 v[46:49], v[178:181], v[206:209], v[46:49]
	v_mfma_f32_16x16x32_bf16 v[38:41], v[146:149], v[214:217], v[38:41]
	v_mfma_f32_16x16x32_bf16 v[30:33], v[178:181], v[214:217], v[30:33]
	v_mfma_f32_16x16x32_bf16 v[22:25], v[146:149], v[222:225], v[22:25]
	v_mfma_f32_16x16x32_bf16 v[14:17], v[178:181], v[222:225], v[14:17]
	v_mfma_f32_16x16x32_bf16 v[6:9], v[146:149], v[230:233], v[6:9]
	v_mfma_f32_16x16x32_bf16 v[2:5], v[178:181], v[230:233], v[2:5]
	v_mfma_f32_16x16x32_bf16 v[54:57], v[160:163], v[210:213], v[54:57]
	v_mfma_f32_16x16x32_bf16 v[46:49], v[186:189], v[210:213], v[46:49]
	v_mfma_f32_16x16x32_bf16 v[38:41], v[160:163], v[218:221], v[38:41]
	v_mfma_f32_16x16x32_bf16 v[30:33], v[186:189], v[218:221], v[30:33]
	v_mfma_f32_16x16x32_bf16 v[22:25], v[160:163], v[226:229], v[22:25]
	v_mfma_f32_16x16x32_bf16 v[14:17], v[186:189], v[226:229], v[14:17]
	v_mfma_f32_16x16x32_bf16 v[6:9], v[160:163], v[234:237], v[6:9]
	v_mfma_f32_16x16x32_bf16 v[2:5], v[186:189], v[234:237], v[2:5]
	s_setprio 0
	s_barrier
	s_add_i32 s84, s84, 2
	s_add_u32 s64, s64, 0x100
	s_addc_u32 s65, s65, 0
	s_add_u32 s82, s82, 0x100
	s_addc_u32 s83, s83, 0
	s_cmpk_gt_u32 s84, 0x7d
	s_cbranch_scc0 .LBB0_1112
	s_and_b64 vcc, exec, s[12:13]
	s_cbranch_vccz .LBB0_1115
	s_barrier

.LBB0_1138:
	s_add_u32 s46, s62, 0xffe00080
	s_addc_u32 s47, s63, -1
	s_add_i32 s48, 0, 0x10000
	s_cmpk_eq_i32 s82, 0x7c
	s_cselect_b32 s65, s17, s47
	s_cselect_b32 s64, s78, s46
	s_cselect_b32 s61, s13, s81
	s_cselect_b32 s60, s79, s80
	s_add_i32 s49, 0, 0x14000
	v_add_u32_e32 v142, s48, v186
	v_add_u32_e32 v164, s49, v186
	ds_read_b128 v[130:133], v142
	ds_read_b128 v[134:137], v142 offset:1024
	ds_read_b128 v[138:141], v142 offset:2048
	ds_read_b128 v[142:145], v142 offset:3072
	ds_read_b128 v[146:149], v164
	ds_read_b128 v[160:163], v164 offset:1024
	ds_read_b128 v[178:181], v164 offset:2048
	ds_read_b128 v[182:185], v164 offset:3072
	v_lshl_add_u64 v[164:165], s[62:63], 0, v[156:157]
	s_add_i32 m0, s71, 0xc000
	ds_read_b128 v[206:209], v188
	ds_read_b128 v[210:213], v188 offset:1024
	ds_read_b128 v[214:217], v188 offset:2048
	ds_read_b128 v[218:221], v188 offset:3072
	ds_read_b128 v[222:225], v188 offset:4096
	ds_read_b128 v[226:229], v188 offset:5120
	ds_read_b128 v[230:233], v188 offset:6144
	ds_read_b128 v[234:237], v188 offset:7168
	global_load_lds_dwordx4 v[164:165], off
	v_lshl_add_u64 v[164:165], s[62:63], 0, v[158:159]
	s_add_i32 m0, s71, 0xe000
	s_nop 0
	global_load_lds_dwordx4 v[164:165], off
	s_waitcnt vmcnt(8)
	s_waitcnt lgkmcnt(0)
	s_setprio 1
	s_waitcnt lgkmcnt(0)
	v_mfma_f32_16x16x32_bf16 v[126:129], v[130:133], v[206:209], v[126:129]
	v_mfma_f32_16x16x32_bf16 v[122:125], v[138:141], v[206:209], v[122:125]
	v_mfma_f32_16x16x32_bf16 v[118:121], v[130:133], v[214:217], v[118:121]
	v_mfma_f32_16x16x32_bf16 v[110:113], v[138:141], v[214:217], v[110:113]
	s_barrier
	v_mfma_f32_16x16x32_bf16 v[94:97], v[130:133], v[222:225], v[94:97]
	v_mfma_f32_16x16x32_bf16 v[90:93], v[138:141], v[222:225], v[90:93]
	v_mfma_f32_16x16x32_bf16 v[82:85], v[130:133], v[230:233], v[82:85]
	v_mfma_f32_16x16x32_bf16 v[74:77], v[138:141], v[230:233], v[74:77]
	v_mfma_f32_16x16x32_bf16 v[126:129], v[134:137], v[210:213], v[126:129]
	v_mfma_f32_16x16x32_bf16 v[122:125], v[142:145], v[210:213], v[122:125]
	v_mfma_f32_16x16x32_bf16 v[118:121], v[134:137], v[218:221], v[118:121]
	v_mfma_f32_16x16x32_bf16 v[110:113], v[142:145], v[218:221], v[110:113]
	v_mfma_f32_16x16x32_bf16 v[94:97], v[134:137], v[226:229], v[94:97]
	v_mfma_f32_16x16x32_bf16 v[90:93], v[142:145], v[226:229], v[90:93]
	v_mfma_f32_16x16x32_bf16 v[82:85], v[134:137], v[234:237], v[82:85]
	v_mfma_f32_16x16x32_bf16 v[74:77], v[142:145], v[234:237], v[74:77]
	s_setprio 0
	s_setprio 1
	v_mfma_f32_16x16x32_bf16 v[114:117], v[146:149], v[206:209], v[114:117]
	v_mfma_f32_16x16x32_bf16 v[106:109], v[178:181], v[206:209], v[106:109]
	v_mfma_f32_16x16x32_bf16 v[102:105], v[146:149], v[214:217], v[102:105]
	v_mfma_f32_16x16x32_bf16 v[98:101], v[178:181], v[214:217], v[98:101]
	v_mfma_f32_16x16x32_bf16 v[86:89], v[146:149], v[222:225], v[86:89]
	v_mfma_f32_16x16x32_bf16 v[78:81], v[178:181], v[222:225], v[78:81]
	v_mfma_f32_16x16x32_bf16 v[70:73], v[146:149], v[230:233], v[70:73]
	v_mfma_f32_16x16x32_bf16 v[66:69], v[178:181], v[230:233], v[66:69]
	v_mfma_f32_16x16x32_bf16 v[114:117], v[160:163], v[210:213], v[114:117]
	v_mfma_f32_16x16x32_bf16 v[106:109], v[182:185], v[210:213], v[106:109]
	v_mfma_f32_16x16x32_bf16 v[102:105], v[160:163], v[218:221], v[102:105]
	v_mfma_f32_16x16x32_bf16 v[98:101], v[182:185], v[218:221], v[98:101]
	v_mfma_f32_16x16x32_bf16 v[86:89], v[160:163], v[226:229], v[86:89]
	v_mfma_f32_16x16x32_bf16 v[78:81], v[182:185], v[226:229], v[78:81]
	v_mfma_f32_16x16x32_bf16 v[70:73], v[160:163], v[234:237], v[70:73]
	v_mfma_f32_16x16x32_bf16 v[66:69], v[182:185], v[234:237], v[66:69]
	s_setprio 0
	s_barrier
	s_add_i32 s46, s48, s70
	v_lshl_add_u64 v[164:165], s[60:61], 0, v[166:167]
	s_mov_b32 m0, s46
	ds_read_b128 v[206:209], v188 offset:16384
	ds_read_b128 v[210:213], v188 offset:17408
	ds_read_b128 v[214:217], v188 offset:18432
	ds_read_b128 v[218:221], v188 offset:19456
	ds_read_b128 v[222:225], v188 offset:20480
	ds_read_b128 v[226:229], v188 offset:21504
	ds_read_b128 v[230:233], v188 offset:22528
	ds_read_b128 v[234:237], v188 offset:23552
	global_load_lds_dwordx4 v[164:165], off
	s_add_i32 m0, s46, 0x2000
	s_add_u32 s46, s60, 0x200000
	v_lshl_add_u64 v[242:243], s[60:61], 0, v[154:155]
	s_addc_u32 s47, s61, 0
	s_add_i32 s48, s49, s70
	global_load_lds_dwordx4 v[242:243], off
	v_lshl_add_u64 v[244:245], s[46:47], 0, v[166:167]
	s_mov_b32 m0, s48
	v_lshl_add_u64 v[246:247], s[64:65], 0, v[152:153]
	global_load_lds_dwordx4 v[244:245], off
	v_lshl_add_u64 v[244:245], s[46:47], 0, v[154:155]
	s_add_i32 m0, s48, 0x2000
	s_nop 0
	global_load_lds_dwordx4 v[244:245], off
	v_lshl_add_u64 v[244:245], s[64:65], 0, v[150:151]
	s_mov_b32 m0, s71
	s_nop 0
	global_load_lds_dwordx4 v[244:245], off
	s_mov_b32 m0, s72
	s_nop 0
	global_load_lds_dwordx4 v[246:247], off
	s_waitcnt vmcnt(8)
	s_waitcnt lgkmcnt(0)
	s_setprio 1
	s_waitcnt lgkmcnt(0)
	v_mfma_f32_16x16x32_bf16 v[62:65], v[130:133], v[206:209], v[62:65]
	v_mfma_f32_16x16x32_bf16 v[58:61], v[138:141], v[206:209], v[58:61]
	v_mfma_f32_16x16x32_bf16 v[50:53], v[130:133], v[214:217], v[50:53]
	v_mfma_f32_16x16x32_bf16 v[42:45], v[138:141], v[214:217], v[42:45]
	s_barrier
	v_mfma_f32_16x16x32_bf16 v[34:37], v[130:133], v[222:225], v[34:37]
	v_mfma_f32_16x16x32_bf16 v[26:29], v[138:141], v[222:225], v[26:29]
	v_mfma_f32_16x16x32_bf16 v[18:21], v[130:133], v[230:233], v[18:21]
	v_mfma_f32_16x16x32_bf16 v[10:13], v[138:141], v[230:233], v[10:13]
	v_mfma_f32_16x16x32_bf16 v[62:65], v[134:137], v[210:213], v[62:65]
	v_mfma_f32_16x16x32_bf16 v[58:61], v[142:145], v[210:213], v[58:61]
	v_mfma_f32_16x16x32_bf16 v[50:53], v[134:137], v[218:221], v[50:53]
	v_mfma_f32_16x16x32_bf16 v[42:45], v[142:145], v[218:221], v[42:45]
	v_mfma_f32_16x16x32_bf16 v[34:37], v[134:137], v[226:229], v[34:37]
	v_mfma_f32_16x16x32_bf16 v[26:29], v[142:145], v[226:229], v[26:29]
	v_mfma_f32_16x16x32_bf16 v[18:21], v[134:137], v[234:237], v[18:21]
	v_mfma_f32_16x16x32_bf16 v[10:13], v[142:145], v[234:237], v[10:13]
	s_setprio 0
	s_setprio 1
	v_mfma_f32_16x16x32_bf16 v[54:57], v[146:149], v[206:209], v[54:57]
	v_mfma_f32_16x16x32_bf16 v[46:49], v[178:181], v[206:209], v[46:49]
	v_mfma_f32_16x16x32_bf16 v[38:41], v[146:149], v[214:217], v[38:41]
	v_mfma_f32_16x16x32_bf16 v[30:33], v[178:181], v[214:217], v[30:33]
	v_mfma_f32_16x16x32_bf16 v[22:25], v[146:149], v[222:225], v[22:25]
	v_mfma_f32_16x16x32_bf16 v[14:17], v[178:181], v[222:225], v[14:17]
	v_mfma_f32_16x16x32_bf16 v[6:9], v[146:149], v[230:233], v[6:9]
	v_mfma_f32_16x16x32_bf16 v[2:5], v[178:181], v[230:233], v[2:5]
	v_mfma_f32_16x16x32_bf16 v[54:57], v[160:163], v[210:213], v[54:57]
	v_mfma_f32_16x16x32_bf16 v[46:49], v[182:185], v[210:213], v[46:49]
	v_mfma_f32_16x16x32_bf16 v[38:41], v[160:163], v[218:221], v[38:41]
	v_mfma_f32_16x16x32_bf16 v[30:33], v[182:185], v[218:221], v[30:33]
	v_mfma_f32_16x16x32_bf16 v[22:25], v[160:163], v[226:229], v[22:25]
	v_mfma_f32_16x16x32_bf16 v[14:17], v[182:185], v[226:229], v[14:17]
	v_mfma_f32_16x16x32_bf16 v[6:9], v[160:163], v[234:237], v[6:9]
	v_mfma_f32_16x16x32_bf16 v[2:5], v[182:185], v[234:237], v[2:5]
	s_setprio 0
	s_barrier
	s_add_i32 s48, 0, 0x18000
	s_add_i32 s49, 0, 0x1c000
	v_add_u32_e32 v142, s48, v186
	v_add_u32_e32 v182, s49, v186
	ds_read_b128 v[130:133], v142
	ds_read_b128 v[134:137], v142 offset:1024
	ds_read_b128 v[138:141], v142 offset:2048
	ds_read_b128 v[142:145], v142 offset:3072
	ds_read_b128 v[146:149], v182
	ds_read_b128 v[160:163], v182 offset:1024
	ds_read_b128 v[178:181], v182 offset:2048
	ds_read_b128 v[182:185], v182 offset:3072
	s_add_u32 s46, s64, 0x200000
	s_addc_u32 s47, s65, 0
	s_mov_b32 m0, s73
	v_lshl_add_u64 v[248:249], s[46:47], 0, v[150:151]
	ds_read_b128 v[206:209], v188 offset:32768
	ds_read_b128 v[210:213], v188 offset:33792
	ds_read_b128 v[214:217], v188 offset:34816
	ds_read_b128 v[218:221], v188 offset:35840
	ds_read_b128 v[222:225], v188 offset:36864
	ds_read_b128 v[226:229], v188 offset:37888
	ds_read_b128 v[230:233], v188 offset:38912
	ds_read_b128 v[234:237], v188 offset:39936
	global_load_lds_dwordx4 v[248:249], off
	v_lshl_add_u64 v[248:249], s[46:47], 0, v[152:153]
	s_mov_b32 m0, s74
	s_nop 0
	global_load_lds_dwordx4 v[248:249], off
	s_waitcnt vmcnt(8)
	s_waitcnt lgkmcnt(0)
	s_setprio 1
	s_waitcnt lgkmcnt(0)
	v_mfma_f32_16x16x32_bf16 v[126:129], v[130:133], v[206:209], v[126:129]
	v_mfma_f32_16x16x32_bf16 v[122:125], v[138:141], v[206:209], v[122:125]
	v_mfma_f32_16x16x32_bf16 v[118:121], v[130:133], v[214:217], v[118:121]
	v_mfma_f32_16x16x32_bf16 v[110:113], v[138:141], v[214:217], v[110:113]
	s_barrier
	v_mfma_f32_16x16x32_bf16 v[94:97], v[130:133], v[222:225], v[94:97]
	v_mfma_f32_16x16x32_bf16 v[90:93], v[138:141], v[222:225], v[90:93]
	v_mfma_f32_16x16x32_bf16 v[82:85], v[130:133], v[230:233], v[82:85]
	v_mfma_f32_16x16x32_bf16 v[74:77], v[138:141], v[230:233], v[74:77]
	v_mfma_f32_16x16x32_bf16 v[126:129], v[134:137], v[210:213], v[126:129]
	v_mfma_f32_16x16x32_bf16 v[122:125], v[142:145], v[210:213], v[122:125]
	v_mfma_f32_16x16x32_bf16 v[118:121], v[134:137], v[218:221], v[118:121]
	v_mfma_f32_16x16x32_bf16 v[110:113], v[142:145], v[218:221], v[110:113]
	v_mfma_f32_16x16x32_bf16 v[94:97], v[134:137], v[226:229], v[94:97]
	v_mfma_f32_16x16x32_bf16 v[90:93], v[142:145], v[226:229], v[90:93]
	v_mfma_f32_16x16x32_bf16 v[82:85], v[134:137], v[234:237], v[82:85]
	v_mfma_f32_16x16x32_bf16 v[74:77], v[142:145], v[234:237], v[74:77]
	s_setprio 0
	s_setprio 1
	v_mfma_f32_16x16x32_bf16 v[114:117], v[146:149], v[206:209], v[114:117]
	v_mfma_f32_16x16x32_bf16 v[106:109], v[178:181], v[206:209], v[106:109]
	v_mfma_f32_16x16x32_bf16 v[102:105], v[146:149], v[214:217], v[102:105]
	v_mfma_f32_16x16x32_bf16 v[98:101], v[178:181], v[214:217], v[98:101]
	v_mfma_f32_16x16x32_bf16 v[86:89], v[146:149], v[222:225], v[86:89]
	v_mfma_f32_16x16x32_bf16 v[78:81], v[178:181], v[222:225], v[78:81]
	v_mfma_f32_16x16x32_bf16 v[70:73], v[146:149], v[230:233], v[70:73]
	v_mfma_f32_16x16x32_bf16 v[66:69], v[178:181], v[230:233], v[66:69]
	v_mfma_f32_16x16x32_bf16 v[114:117], v[160:163], v[210:213], v[114:117]
	v_mfma_f32_16x16x32_bf16 v[106:109], v[182:185], v[210:213], v[106:109]
	v_mfma_f32_16x16x32_bf16 v[102:105], v[160:163], v[218:221], v[102:105]
	v_mfma_f32_16x16x32_bf16 v[98:101], v[182:185], v[218:221], v[98:101]
	v_mfma_f32_16x16x32_bf16 v[86:89], v[160:163], v[226:229], v[86:89]
	v_mfma_f32_16x16x32_bf16 v[78:81], v[182:185], v[226:229], v[78:81]
	v_mfma_f32_16x16x32_bf16 v[70:73], v[160:163], v[234:237], v[70:73]
	v_mfma_f32_16x16x32_bf16 v[66:69], v[182:185], v[234:237], v[66:69]
	s_setprio 0
	s_barrier
	s_add_i32 s46, s48, s70
	v_lshl_add_u64 v[164:165], v[164:165], 0, s[42:43]
	s_mov_b32 m0, s46
	ds_read_b128 v[206:209], v188 offset:49152
	ds_read_b128 v[210:213], v188 offset:50176
	ds_read_b128 v[214:217], v188 offset:51200
	ds_read_b128 v[218:221], v188 offset:52224
	ds_read_b128 v[222:225], v188 offset:53248
	ds_read_b128 v[226:229], v188 offset:54272
	ds_read_b128 v[230:233], v188 offset:55296
	ds_read_b128 v[234:237], v188 offset:56320
	global_load_lds_dwordx4 v[164:165], off
	s_add_i32 m0, s46, 0x2000
	s_add_u32 s46, s60, 0x200080
	v_lshl_add_u64 v[164:165], v[242:243], 0, s[42:43]
	s_addc_u32 s47, s61, 0
	s_add_i32 s48, s49, s70
	global_load_lds_dwordx4 v[164:165], off
	v_lshl_add_u64 v[164:165], s[46:47], 0, v[166:167]
	s_mov_b32 m0, s48
	s_nop 0
	global_load_lds_dwordx4 v[164:165], off
	v_lshl_add_u64 v[164:165], s[46:47], 0, v[154:155]
	s_add_i32 m0, s48, 0x2000
	s_nop 0
	global_load_lds_dwordx4 v[164:165], off
	v_lshl_add_u64 v[164:165], v[244:245], 0, s[42:43]
	s_mov_b32 m0, s75
	s_nop 0
	global_load_lds_dwordx4 v[164:165], off
	v_lshl_add_u64 v[164:165], v[246:247], 0, s[42:43]
	s_mov_b32 m0, s76
	s_nop 0
	global_load_lds_dwordx4 v[164:165], off
	s_waitcnt vmcnt(8)
	s_waitcnt lgkmcnt(0)
	s_setprio 1
	s_waitcnt lgkmcnt(0)
	v_mfma_f32_16x16x32_bf16 v[62:65], v[130:133], v[206:209], v[62:65]
	v_mfma_f32_16x16x32_bf16 v[58:61], v[138:141], v[206:209], v[58:61]
	v_mfma_f32_16x16x32_bf16 v[50:53], v[130:133], v[214:217], v[50:53]
	v_mfma_f32_16x16x32_bf16 v[42:45], v[138:141], v[214:217], v[42:45]
	s_barrier
	v_mfma_f32_16x16x32_bf16 v[34:37], v[130:133], v[222:225], v[34:37]
	v_mfma_f32_16x16x32_bf16 v[26:29], v[138:141], v[222:225], v[26:29]
	v_mfma_f32_16x16x32_bf16 v[18:21], v[130:133], v[230:233], v[18:21]
	v_mfma_f32_16x16x32_bf16 v[10:13], v[138:141], v[230:233], v[10:13]
	v_mfma_f32_16x16x32_bf16 v[62:65], v[134:137], v[210:213], v[62:65]
	v_mfma_f32_16x16x32_bf16 v[58:61], v[142:145], v[210:213], v[58:61]
	v_mfma_f32_16x16x32_bf16 v[50:53], v[134:137], v[218:221], v[50:53]
	v_mfma_f32_16x16x32_bf16 v[42:45], v[142:145], v[218:221], v[42:45]
	v_mfma_f32_16x16x32_bf16 v[34:37], v[134:137], v[226:229], v[34:37]
	v_mfma_f32_16x16x32_bf16 v[26:29], v[142:145], v[226:229], v[26:29]
	v_mfma_f32_16x16x32_bf16 v[18:21], v[134:137], v[234:237], v[18:21]
	v_mfma_f32_16x16x32_bf16 v[10:13], v[142:145], v[234:237], v[10:13]
	s_setprio 0
	s_setprio 1
	v_mfma_f32_16x16x32_bf16 v[54:57], v[146:149], v[206:209], v[54:57]
	v_mfma_f32_16x16x32_bf16 v[46:49], v[178:181], v[206:209], v[46:49]
	v_mfma_f32_16x16x32_bf16 v[38:41], v[146:149], v[214:217], v[38:41]
	v_mfma_f32_16x16x32_bf16 v[30:33], v[178:181], v[214:217], v[30:33]
	v_mfma_f32_16x16x32_bf16 v[22:25], v[146:149], v[222:225], v[22:25]
	v_mfma_f32_16x16x32_bf16 v[14:17], v[178:181], v[222:225], v[14:17]
	v_mfma_f32_16x16x32_bf16 v[6:9], v[146:149], v[230:233], v[6:9]
	v_mfma_f32_16x16x32_bf16 v[2:5], v[178:181], v[230:233], v[2:5]
	v_mfma_f32_16x16x32_bf16 v[54:57], v[160:163], v[210:213], v[54:57]
	v_mfma_f32_16x16x32_bf16 v[46:49], v[182:185], v[210:213], v[46:49]
	v_mfma_f32_16x16x32_bf16 v[38:41], v[160:163], v[218:221], v[38:41]
	v_mfma_f32_16x16x32_bf16 v[30:33], v[182:185], v[218:221], v[30:33]
	v_mfma_f32_16x16x32_bf16 v[22:25], v[160:163], v[226:229], v[22:25]
	v_mfma_f32_16x16x32_bf16 v[14:17], v[182:185], v[226:229], v[14:17]
	v_mfma_f32_16x16x32_bf16 v[6:9], v[160:163], v[234:237], v[6:9]
	v_mfma_f32_16x16x32_bf16 v[2:5], v[182:185], v[234:237], v[2:5]
	s_setprio 0
	s_barrier
	s_add_i32 s82, s82, 2
	s_add_u32 s62, s62, 0x100
	s_addc_u32 s63, s63, 0
	s_add_u32 s80, s80, 0x100
	s_addc_u32 s81, s81, 0
	s_cmpk_gt_u32 s82, 0x7d
	s_cbranch_scc0 .LBB0_1138
	s_and_b64 vcc, exec, s[10:11]
	s_cbranch_vccz .LBB0_1141
	s_barrier
